# GEMM K-loops: priority inverted (load segment at prio 1, MFMA block at prio 0)
# speedup vs baseline: 1.0029x; 1.0029x over previous
.LBB0_395:
	ds_read_b128 v[152:155], v149
	ds_read_b128 v[156:159], v149 offset:1024
	ds_read_b128 v[160:163], v149 offset:2048
	ds_read_b128 v[164:167], v149 offset:3072
	ds_read_b128 v[168:171], v150
	ds_read_b128 v[172:175], v150 offset:1024
	ds_read_b128 v[176:179], v150 offset:2048
	ds_read_b128 v[180:183], v150 offset:3072
	s_add_u32 s24, s22, 0xfffc0080
	s_addc_u32 s25, s23, -1
	s_cmp_eq_u32 s45, 12
	s_cselect_b32 s27, s17, s25
	s_cselect_b32 s26, s41, s24
	s_cselect_b32 s25, s15, s44
	s_cselect_b32 s24, s42, s43
	v_lshl_add_u64 v[216:217], s[22:23], 0, v[138:139]
	s_add_i32 m0, s13, 0xc000
	ds_read_b128 v[184:187], v151
	ds_read_b128 v[188:191], v151 offset:1024
	ds_read_b128 v[192:195], v151 offset:2048
	ds_read_b128 v[196:199], v151 offset:3072
	ds_read_b128 v[200:203], v151 offset:4096
	ds_read_b128 v[204:207], v151 offset:5120
	ds_read_b128 v[208:211], v151 offset:6144
	ds_read_b128 v[212:215], v151 offset:7168
	global_load_lds_dwordx4 v[216:217], off
	v_lshl_add_u64 v[216:217], s[22:23], 0, v[140:141]
	s_add_i32 m0, s13, 0xe000
	s_nop 0
	global_load_lds_dwordx4 v[216:217], off
	s_waitcnt vmcnt(8)
	s_waitcnt lgkmcnt(0)
	s_barrier
	s_setprio 0
	s_waitcnt lgkmcnt(0)
	v_mfma_f32_16x16x32_bf16 v[126:129], v[152:155], v[184:187], v[126:129]
	v_mfma_f32_16x16x32_bf16 v[122:125], v[160:163], v[184:187], v[122:125]
	v_mfma_f32_16x16x32_bf16 v[118:121], v[152:155], v[192:195], v[118:121]
	v_mfma_f32_16x16x32_bf16 v[114:117], v[160:163], v[192:195], v[114:117]
	v_mfma_f32_16x16x32_bf16 v[102:105], v[152:155], v[200:203], v[102:105]
	v_mfma_f32_16x16x32_bf16 v[98:101], v[160:163], v[200:203], v[98:101]
	v_mfma_f32_16x16x32_bf16 v[86:89], v[152:155], v[208:211], v[86:89]
	v_mfma_f32_16x16x32_bf16 v[82:85], v[160:163], v[208:211], v[82:85]
	v_mfma_f32_16x16x32_bf16 v[126:129], v[156:159], v[188:191], v[126:129]
	v_mfma_f32_16x16x32_bf16 v[122:125], v[164:167], v[188:191], v[122:125]
	v_mfma_f32_16x16x32_bf16 v[118:121], v[156:159], v[196:199], v[118:121]
	v_mfma_f32_16x16x32_bf16 v[114:117], v[164:167], v[196:199], v[114:117]
	v_mfma_f32_16x16x32_bf16 v[102:105], v[156:159], v[204:207], v[102:105]
	v_mfma_f32_16x16x32_bf16 v[98:101], v[164:167], v[204:207], v[98:101]
	v_mfma_f32_16x16x32_bf16 v[86:89], v[156:159], v[212:215], v[86:89]
	v_mfma_f32_16x16x32_bf16 v[82:85], v[164:167], v[212:215], v[82:85]
	v_mfma_f32_16x16x32_bf16 v[110:113], v[168:171], v[184:187], v[110:113]
	v_mfma_f32_16x16x32_bf16 v[106:109], v[176:179], v[184:187], v[106:109]
	v_mfma_f32_16x16x32_bf16 v[94:97], v[168:171], v[192:195], v[94:97]
	v_mfma_f32_16x16x32_bf16 v[90:93], v[176:179], v[192:195], v[90:93]
	v_mfma_f32_16x16x32_bf16 v[78:81], v[168:171], v[200:203], v[78:81]
	v_mfma_f32_16x16x32_bf16 v[74:77], v[176:179], v[200:203], v[74:77]
	v_mfma_f32_16x16x32_bf16 v[70:73], v[168:171], v[208:211], v[70:73]
	v_mfma_f32_16x16x32_bf16 v[66:69], v[176:179], v[208:211], v[66:69]
	v_mfma_f32_16x16x32_bf16 v[110:113], v[172:175], v[188:191], v[110:113]
	v_mfma_f32_16x16x32_bf16 v[106:109], v[180:183], v[188:191], v[106:109]
	v_mfma_f32_16x16x32_bf16 v[94:97], v[172:175], v[196:199], v[94:97]
	v_mfma_f32_16x16x32_bf16 v[90:93], v[180:183], v[196:199], v[90:93]
	v_mfma_f32_16x16x32_bf16 v[78:81], v[172:175], v[204:207], v[78:81]
	v_mfma_f32_16x16x32_bf16 v[74:77], v[180:183], v[204:207], v[74:77]
	v_mfma_f32_16x16x32_bf16 v[70:73], v[172:175], v[212:215], v[70:73]
	v_mfma_f32_16x16x32_bf16 v[66:69], v[180:183], v[212:215], v[66:69]
	s_setprio 1
	s_barrier
	s_add_i32 s46, s37, s2
	v_lshl_add_u64 v[216:217], s[24:25], 0, v[134:135]
	s_mov_b32 m0, s46
	ds_read_b128 v[184:187], v151 offset:16384
	ds_read_b128 v[188:191], v151 offset:17408
	ds_read_b128 v[192:195], v151 offset:18432
	ds_read_b128 v[196:199], v151 offset:19456
	ds_read_b128 v[200:203], v151 offset:20480
	ds_read_b128 v[204:207], v151 offset:21504
	ds_read_b128 v[208:211], v151 offset:22528
	ds_read_b128 v[212:215], v151 offset:23552
	global_load_lds_dwordx4 v[216:217], off
	s_add_i32 m0, s46, 0x2000
	s_add_u32 s46, s24, 0x40000
	v_lshl_add_u64 v[218:219], s[24:25], 0, v[130:131]
	s_addc_u32 s47, s25, 0
	s_add_i32 s48, s38, s2
	global_load_lds_dwordx4 v[218:219], off
	v_lshl_add_u64 v[220:221], s[46:47], 0, v[134:135]
	s_mov_b32 m0, s48
	v_lshl_add_u64 v[222:223], s[26:27], 0, v[132:133]
	global_load_lds_dwordx4 v[220:221], off
	v_lshl_add_u64 v[220:221], s[46:47], 0, v[130:131]
	s_add_i32 m0, s48, 0x2000
	s_nop 0
	global_load_lds_dwordx4 v[220:221], off
	v_lshl_add_u64 v[220:221], s[26:27], 0, v[136:137]
	s_mov_b32 m0, s13
	s_nop 0
	global_load_lds_dwordx4 v[220:221], off
	s_mov_b32 m0, s28
	s_nop 0
	global_load_lds_dwordx4 v[222:223], off
	s_waitcnt vmcnt(8)
	s_waitcnt lgkmcnt(0)
	s_barrier
	s_setprio 0
	s_waitcnt lgkmcnt(0)
	v_mfma_f32_16x16x32_bf16 v[62:65], v[152:155], v[184:187], v[62:65]
	v_mfma_f32_16x16x32_bf16 v[58:61], v[160:163], v[184:187], v[58:61]
	v_mfma_f32_16x16x32_bf16 v[54:57], v[152:155], v[192:195], v[54:57]
	v_mfma_f32_16x16x32_bf16 v[50:53], v[160:163], v[192:195], v[50:53]
	v_mfma_f32_16x16x32_bf16 v[38:41], v[152:155], v[200:203], v[38:41]
	v_mfma_f32_16x16x32_bf16 v[34:37], v[160:163], v[200:203], v[34:37]
	v_mfma_f32_16x16x32_bf16 v[22:25], v[152:155], v[208:211], v[22:25]
	v_mfma_f32_16x16x32_bf16 v[18:21], v[160:163], v[208:211], v[18:21]
	v_mfma_f32_16x16x32_bf16 v[62:65], v[156:159], v[188:191], v[62:65]
	v_mfma_f32_16x16x32_bf16 v[58:61], v[164:167], v[188:191], v[58:61]
	v_mfma_f32_16x16x32_bf16 v[54:57], v[156:159], v[196:199], v[54:57]
	v_mfma_f32_16x16x32_bf16 v[50:53], v[164:167], v[196:199], v[50:53]
	v_mfma_f32_16x16x32_bf16 v[38:41], v[156:159], v[204:207], v[38:41]
	v_mfma_f32_16x16x32_bf16 v[34:37], v[164:167], v[204:207], v[34:37]
	v_mfma_f32_16x16x32_bf16 v[22:25], v[156:159], v[212:215], v[22:25]
	v_mfma_f32_16x16x32_bf16 v[18:21], v[164:167], v[212:215], v[18:21]
	v_mfma_f32_16x16x32_bf16 v[46:49], v[168:171], v[184:187], v[46:49]
	v_mfma_f32_16x16x32_bf16 v[42:45], v[176:179], v[184:187], v[42:45]
	v_mfma_f32_16x16x32_bf16 v[30:33], v[168:171], v[192:195], v[30:33]
	v_mfma_f32_16x16x32_bf16 v[26:29], v[176:179], v[192:195], v[26:29]
	v_mfma_f32_16x16x32_bf16 v[14:17], v[168:171], v[200:203], v[14:17]
	v_mfma_f32_16x16x32_bf16 v[10:13], v[176:179], v[200:203], v[10:13]
	v_mfma_f32_16x16x32_bf16 v[6:9], v[168:171], v[208:211], v[6:9]
	v_mfma_f32_16x16x32_bf16 v[2:5], v[176:179], v[208:211], v[2:5]
	v_mfma_f32_16x16x32_bf16 v[46:49], v[172:175], v[188:191], v[46:49]
	v_mfma_f32_16x16x32_bf16 v[42:45], v[180:183], v[188:191], v[42:45]
	v_mfma_f32_16x16x32_bf16 v[30:33], v[172:175], v[196:199], v[30:33]
	v_mfma_f32_16x16x32_bf16 v[26:29], v[180:183], v[196:199], v[26:29]
	v_mfma_f32_16x16x32_bf16 v[14:17], v[172:175], v[204:207], v[14:17]
	v_mfma_f32_16x16x32_bf16 v[10:13], v[180:183], v[204:207], v[10:13]
	v_mfma_f32_16x16x32_bf16 v[6:9], v[172:175], v[212:215], v[6:9]
	v_mfma_f32_16x16x32_bf16 v[2:5], v[180:183], v[212:215], v[2:5]
	s_setprio 1
	s_barrier
	s_add_i32 s46, 0, 0x18000
	s_add_i32 s47, 0, 0x1c000
	v_add_u32_e32 v164, s46, v147
	v_add_u32_e32 v180, s47, v147
	ds_read_b128 v[152:155], v164
	ds_read_b128 v[156:159], v164 offset:1024
	ds_read_b128 v[160:163], v164 offset:2048
	ds_read_b128 v[164:167], v164 offset:3072
	ds_read_b128 v[168:171], v180
	ds_read_b128 v[172:175], v180 offset:1024
	ds_read_b128 v[176:179], v180 offset:2048
	ds_read_b128 v[180:183], v180 offset:3072
	s_add_u32 s26, s26, 0x40000
	s_addc_u32 s27, s27, 0
	s_mov_b32 m0, s29
	v_lshl_add_u64 v[224:225], s[26:27], 0, v[136:137]
	ds_read_b128 v[184:187], v151 offset:32768
	ds_read_b128 v[188:191], v151 offset:33792
	ds_read_b128 v[192:195], v151 offset:34816
	ds_read_b128 v[196:199], v151 offset:35840
	ds_read_b128 v[200:203], v151 offset:36864
	ds_read_b128 v[204:207], v151 offset:37888
	ds_read_b128 v[208:211], v151 offset:38912
	ds_read_b128 v[212:215], v151 offset:39936
	global_load_lds_dwordx4 v[224:225], off
	v_lshl_add_u64 v[224:225], s[26:27], 0, v[132:133]
	s_mov_b32 m0, s30
	s_nop 0
	global_load_lds_dwordx4 v[224:225], off
	s_waitcnt vmcnt(8)
	s_waitcnt lgkmcnt(0)
	s_barrier
	s_setprio 0
	s_waitcnt lgkmcnt(0)
	v_mfma_f32_16x16x32_bf16 v[126:129], v[152:155], v[184:187], v[126:129]
	v_mfma_f32_16x16x32_bf16 v[122:125], v[160:163], v[184:187], v[122:125]
	v_mfma_f32_16x16x32_bf16 v[118:121], v[152:155], v[192:195], v[118:121]
	v_mfma_f32_16x16x32_bf16 v[114:117], v[160:163], v[192:195], v[114:117]
	v_mfma_f32_16x16x32_bf16 v[102:105], v[152:155], v[200:203], v[102:105]
	v_mfma_f32_16x16x32_bf16 v[98:101], v[160:163], v[200:203], v[98:101]
	v_mfma_f32_16x16x32_bf16 v[86:89], v[152:155], v[208:211], v[86:89]
	v_mfma_f32_16x16x32_bf16 v[82:85], v[160:163], v[208:211], v[82:85]
	v_mfma_f32_16x16x32_bf16 v[126:129], v[156:159], v[188:191], v[126:129]
	v_mfma_f32_16x16x32_bf16 v[122:125], v[164:167], v[188:191], v[122:125]
	v_mfma_f32_16x16x32_bf16 v[118:121], v[156:159], v[196:199], v[118:121]
	v_mfma_f32_16x16x32_bf16 v[114:117], v[164:167], v[196:199], v[114:117]
	v_mfma_f32_16x16x32_bf16 v[102:105], v[156:159], v[204:207], v[102:105]
	v_mfma_f32_16x16x32_bf16 v[98:101], v[164:167], v[204:207], v[98:101]
	v_mfma_f32_16x16x32_bf16 v[86:89], v[156:159], v[212:215], v[86:89]
	v_mfma_f32_16x16x32_bf16 v[82:85], v[164:167], v[212:215], v[82:85]
	v_mfma_f32_16x16x32_bf16 v[110:113], v[168:171], v[184:187], v[110:113]
	v_mfma_f32_16x16x32_bf16 v[106:109], v[176:179], v[184:187], v[106:109]
	v_mfma_f32_16x16x32_bf16 v[94:97], v[168:171], v[192:195], v[94:97]
	v_mfma_f32_16x16x32_bf16 v[90:93], v[176:179], v[192:195], v[90:93]
	v_mfma_f32_16x16x32_bf16 v[78:81], v[168:171], v[200:203], v[78:81]
	v_mfma_f32_16x16x32_bf16 v[74:77], v[176:179], v[200:203], v[74:77]
	v_mfma_f32_16x16x32_bf16 v[70:73], v[168:171], v[208:211], v[70:73]
	v_mfma_f32_16x16x32_bf16 v[66:69], v[176:179], v[208:211], v[66:69]
	v_mfma_f32_16x16x32_bf16 v[110:113], v[172:175], v[188:191], v[110:113]
	v_mfma_f32_16x16x32_bf16 v[106:109], v[180:183], v[188:191], v[106:109]
	v_mfma_f32_16x16x32_bf16 v[94:97], v[172:175], v[196:199], v[94:97]
	v_mfma_f32_16x16x32_bf16 v[90:93], v[180:183], v[196:199], v[90:93]
	v_mfma_f32_16x16x32_bf16 v[78:81], v[172:175], v[204:207], v[78:81]
	v_mfma_f32_16x16x32_bf16 v[74:77], v[180:183], v[204:207], v[74:77]
	v_mfma_f32_16x16x32_bf16 v[70:73], v[172:175], v[212:215], v[70:73]
	v_mfma_f32_16x16x32_bf16 v[66:69], v[180:183], v[212:215], v[66:69]
	s_setprio 1
	s_barrier
	s_add_i32 s26, s46, s2
	v_lshl_add_u64 v[216:217], v[216:217], 0, s[6:7]
	s_mov_b32 m0, s26
	ds_read_b128 v[184:187], v151 offset:49152
	ds_read_b128 v[188:191], v151 offset:50176
	ds_read_b128 v[192:195], v151 offset:51200
	ds_read_b128 v[196:199], v151 offset:52224
	ds_read_b128 v[200:203], v151 offset:53248
	ds_read_b128 v[204:207], v151 offset:54272
	ds_read_b128 v[208:211], v151 offset:55296
	ds_read_b128 v[212:215], v151 offset:56320
	global_load_lds_dwordx4 v[216:217], off
	s_add_i32 m0, s26, 0x2000
	s_add_u32 s24, s24, 0x40080
	v_lshl_add_u64 v[216:217], v[218:219], 0, s[6:7]
	s_addc_u32 s25, s25, 0
	s_add_i32 s26, s47, s2
	global_load_lds_dwordx4 v[216:217], off
	v_lshl_add_u64 v[216:217], s[24:25], 0, v[134:135]
	s_mov_b32 m0, s26
	s_nop 0
	global_load_lds_dwordx4 v[216:217], off
	v_lshl_add_u64 v[216:217], s[24:25], 0, v[130:131]
	s_add_i32 m0, s26, 0x2000
	s_nop 0
	global_load_lds_dwordx4 v[216:217], off
	v_lshl_add_u64 v[216:217], v[220:221], 0, s[6:7]
	s_mov_b32 m0, s34
	s_nop 0
	global_load_lds_dwordx4 v[216:217], off
	v_lshl_add_u64 v[216:217], v[222:223], 0, s[6:7]
	s_mov_b32 m0, s35
	s_nop 0
	global_load_lds_dwordx4 v[216:217], off
	s_waitcnt vmcnt(8)
	s_waitcnt lgkmcnt(0)
	s_barrier
	s_setprio 0
	s_waitcnt lgkmcnt(0)
	v_mfma_f32_16x16x32_bf16 v[62:65], v[152:155], v[184:187], v[62:65]
	v_mfma_f32_16x16x32_bf16 v[58:61], v[160:163], v[184:187], v[58:61]
	v_mfma_f32_16x16x32_bf16 v[54:57], v[152:155], v[192:195], v[54:57]
	v_mfma_f32_16x16x32_bf16 v[50:53], v[160:163], v[192:195], v[50:53]
	v_mfma_f32_16x16x32_bf16 v[38:41], v[152:155], v[200:203], v[38:41]
	v_mfma_f32_16x16x32_bf16 v[34:37], v[160:163], v[200:203], v[34:37]
	v_mfma_f32_16x16x32_bf16 v[22:25], v[152:155], v[208:211], v[22:25]
	v_mfma_f32_16x16x32_bf16 v[18:21], v[160:163], v[208:211], v[18:21]
	v_mfma_f32_16x16x32_bf16 v[62:65], v[156:159], v[188:191], v[62:65]
	v_mfma_f32_16x16x32_bf16 v[58:61], v[164:167], v[188:191], v[58:61]
	v_mfma_f32_16x16x32_bf16 v[54:57], v[156:159], v[196:199], v[54:57]
	v_mfma_f32_16x16x32_bf16 v[50:53], v[164:167], v[196:199], v[50:53]
	v_mfma_f32_16x16x32_bf16 v[38:41], v[156:159], v[204:207], v[38:41]
	v_mfma_f32_16x16x32_bf16 v[34:37], v[164:167], v[204:207], v[34:37]
	v_mfma_f32_16x16x32_bf16 v[22:25], v[156:159], v[212:215], v[22:25]
	v_mfma_f32_16x16x32_bf16 v[18:21], v[164:167], v[212:215], v[18:21]
	v_mfma_f32_16x16x32_bf16 v[46:49], v[168:171], v[184:187], v[46:49]
	v_mfma_f32_16x16x32_bf16 v[42:45], v[176:179], v[184:187], v[42:45]
	v_mfma_f32_16x16x32_bf16 v[30:33], v[168:171], v[192:195], v[30:33]
	v_mfma_f32_16x16x32_bf16 v[26:29], v[176:179], v[192:195], v[26:29]
	v_mfma_f32_16x16x32_bf16 v[14:17], v[168:171], v[200:203], v[14:17]
	v_mfma_f32_16x16x32_bf16 v[10:13], v[176:179], v[200:203], v[10:13]
	v_mfma_f32_16x16x32_bf16 v[6:9], v[168:171], v[208:211], v[6:9]
	v_mfma_f32_16x16x32_bf16 v[2:5], v[176:179], v[208:211], v[2:5]
	v_mfma_f32_16x16x32_bf16 v[46:49], v[172:175], v[188:191], v[46:49]
	v_mfma_f32_16x16x32_bf16 v[42:45], v[180:183], v[188:191], v[42:45]
	v_mfma_f32_16x16x32_bf16 v[30:33], v[172:175], v[196:199], v[30:33]
	v_mfma_f32_16x16x32_bf16 v[26:29], v[180:183], v[196:199], v[26:29]
	v_mfma_f32_16x16x32_bf16 v[14:17], v[172:175], v[204:207], v[14:17]
	v_mfma_f32_16x16x32_bf16 v[10:13], v[180:183], v[204:207], v[10:13]
	v_mfma_f32_16x16x32_bf16 v[6:9], v[172:175], v[212:215], v[6:9]
	v_mfma_f32_16x16x32_bf16 v[2:5], v[180:183], v[212:215], v[2:5]
	s_setprio 1
	s_barrier
	s_add_i32 s45, s45, 2
	s_add_u32 s22, s22, 0x100
	s_addc_u32 s23, s23, 0
	s_add_u32 s43, s43, 0x100
	s_addc_u32 s44, s44, 0
	s_cmp_gt_u32 s45, 13
	s_cbranch_scc0 .LBB0_395
	s_and_b64 vcc, exec, s[8:9]
	s_cbranch_vccz .LBB0_398
	s_barrier

.LBB0_419:
	ds_read_b128 v[144:147], v141
	ds_read_b128 v[148:151], v141 offset:1024
	ds_read_b128 v[152:155], v141 offset:2048
	ds_read_b128 v[156:159], v141 offset:3072
	ds_read_b128 v[160:163], v142
	ds_read_b128 v[164:167], v142 offset:1024
	ds_read_b128 v[168:171], v142 offset:2048
	ds_read_b128 v[172:175], v142 offset:3072
	s_add_u32 s24, s22, 0xfffc0080
	s_addc_u32 s25, s23, -1
	s_cmp_eq_u32 s43, 12
	s_cselect_b32 s27, s10, s25
	s_cselect_b32 s26, s11, s24
	s_cselect_b32 s25, s15, s42
	s_cselect_b32 s24, s17, s41
	v_lshl_add_u64 v[208:209], s[22:23], 0, v[134:135]
	s_add_i32 m0, s29, 0xc000
	ds_read_b128 v[176:179], v143
	ds_read_b128 v[180:183], v143 offset:1024
	ds_read_b128 v[184:187], v143 offset:2048
	ds_read_b128 v[188:191], v143 offset:3072
	ds_read_b128 v[192:195], v143 offset:4096
	ds_read_b128 v[196:199], v143 offset:5120
	ds_read_b128 v[200:203], v143 offset:6144
	ds_read_b128 v[204:207], v143 offset:7168
	global_load_lds_dwordx4 v[208:209], off
	v_lshl_add_u64 v[208:209], s[22:23], 0, v[136:137]
	s_add_i32 m0, s29, 0xe000
	s_nop 0
	global_load_lds_dwordx4 v[208:209], off
	s_waitcnt vmcnt(8)
	s_waitcnt lgkmcnt(0)
	s_barrier
	s_setprio 0
	s_waitcnt lgkmcnt(0)
	v_mfma_f32_16x16x32_bf16 v[126:129], v[144:147], v[176:179], v[126:129]
	v_mfma_f32_16x16x32_bf16 v[122:125], v[152:155], v[176:179], v[122:125]
	v_mfma_f32_16x16x32_bf16 v[118:121], v[144:147], v[184:187], v[118:121]
	v_mfma_f32_16x16x32_bf16 v[114:117], v[152:155], v[184:187], v[114:117]
	v_mfma_f32_16x16x32_bf16 v[106:109], v[144:147], v[192:195], v[106:109]
	v_mfma_f32_16x16x32_bf16 v[98:101], v[152:155], v[192:195], v[98:101]
	v_mfma_f32_16x16x32_bf16 v[90:93], v[144:147], v[200:203], v[90:93]
	v_mfma_f32_16x16x32_bf16 v[82:85], v[152:155], v[200:203], v[82:85]
	v_mfma_f32_16x16x32_bf16 v[126:129], v[148:151], v[180:183], v[126:129]
	v_mfma_f32_16x16x32_bf16 v[122:125], v[156:159], v[180:183], v[122:125]
	v_mfma_f32_16x16x32_bf16 v[118:121], v[148:151], v[188:191], v[118:121]
	v_mfma_f32_16x16x32_bf16 v[114:117], v[156:159], v[188:191], v[114:117]
	v_mfma_f32_16x16x32_bf16 v[106:109], v[148:151], v[196:199], v[106:109]
	v_mfma_f32_16x16x32_bf16 v[98:101], v[156:159], v[196:199], v[98:101]
	v_mfma_f32_16x16x32_bf16 v[90:93], v[148:151], v[204:207], v[90:93]
	v_mfma_f32_16x16x32_bf16 v[82:85], v[156:159], v[204:207], v[82:85]
	v_mfma_f32_16x16x32_bf16 v[110:113], v[160:163], v[176:179], v[110:113]
	v_mfma_f32_16x16x32_bf16 v[102:105], v[168:171], v[176:179], v[102:105]
	v_mfma_f32_16x16x32_bf16 v[94:97], v[160:163], v[184:187], v[94:97]
	v_mfma_f32_16x16x32_bf16 v[86:89], v[168:171], v[184:187], v[86:89]
	v_mfma_f32_16x16x32_bf16 v[78:81], v[160:163], v[192:195], v[78:81]
	v_mfma_f32_16x16x32_bf16 v[74:77], v[168:171], v[192:195], v[74:77]
	v_mfma_f32_16x16x32_bf16 v[70:73], v[160:163], v[200:203], v[70:73]
	v_mfma_f32_16x16x32_bf16 v[66:69], v[168:171], v[200:203], v[66:69]
	v_mfma_f32_16x16x32_bf16 v[110:113], v[164:167], v[180:183], v[110:113]
	v_mfma_f32_16x16x32_bf16 v[102:105], v[172:175], v[180:183], v[102:105]
	v_mfma_f32_16x16x32_bf16 v[94:97], v[164:167], v[188:191], v[94:97]
	v_mfma_f32_16x16x32_bf16 v[86:89], v[172:175], v[188:191], v[86:89]
	v_mfma_f32_16x16x32_bf16 v[78:81], v[164:167], v[196:199], v[78:81]
	v_mfma_f32_16x16x32_bf16 v[74:77], v[172:175], v[196:199], v[74:77]
	v_mfma_f32_16x16x32_bf16 v[70:73], v[164:167], v[204:207], v[70:73]
	v_mfma_f32_16x16x32_bf16 v[66:69], v[172:175], v[204:207], v[66:69]
	s_setprio 1
	s_barrier
	s_add_i32 s44, s39, s28
	v_lshl_add_u64 v[208:209], s[24:25], 0, v[130:131]
	s_mov_b32 m0, s44
	ds_read_b128 v[176:179], v143 offset:16384
	ds_read_b128 v[180:183], v143 offset:17408
	ds_read_b128 v[184:187], v143 offset:18432
	ds_read_b128 v[188:191], v143 offset:19456
	ds_read_b128 v[192:195], v143 offset:20480
	ds_read_b128 v[196:199], v143 offset:21504
	ds_read_b128 v[200:203], v143 offset:22528
	ds_read_b128 v[204:207], v143 offset:23552
	global_load_lds_dwordx4 v[208:209], off
	s_add_i32 m0, s44, 0x2000
	s_add_u32 s44, s24, 0x40000
	v_lshl_add_u64 v[210:211], s[24:25], 0, v[132:133]
	s_addc_u32 s45, s25, 0
	s_add_i32 s46, s40, s28
	global_load_lds_dwordx4 v[210:211], off
	v_lshl_add_u64 v[212:213], s[44:45], 0, v[130:131]
	s_mov_b32 m0, s46
	v_lshl_add_u64 v[214:215], s[26:27], 0, v[132:133]
	global_load_lds_dwordx4 v[212:213], off
	v_lshl_add_u64 v[212:213], s[44:45], 0, v[132:133]
	s_add_i32 m0, s46, 0x2000
	s_nop 0
	global_load_lds_dwordx4 v[212:213], off
	v_lshl_add_u64 v[212:213], s[26:27], 0, v[130:131]
	s_mov_b32 m0, s29
	s_nop 0
	global_load_lds_dwordx4 v[212:213], off
	s_mov_b32 m0, s30
	s_nop 0
	global_load_lds_dwordx4 v[214:215], off
	s_waitcnt vmcnt(8)
	s_waitcnt lgkmcnt(0)
	s_barrier
	s_setprio 0
	s_waitcnt lgkmcnt(0)
	v_mfma_f32_16x16x32_bf16 v[62:65], v[144:147], v[176:179], v[62:65]
	v_mfma_f32_16x16x32_bf16 v[58:61], v[152:155], v[176:179], v[58:61]
	v_mfma_f32_16x16x32_bf16 v[54:57], v[144:147], v[184:187], v[54:57]
	v_mfma_f32_16x16x32_bf16 v[50:53], v[152:155], v[184:187], v[50:53]
	v_mfma_f32_16x16x32_bf16 v[38:41], v[144:147], v[192:195], v[38:41]
	v_mfma_f32_16x16x32_bf16 v[34:37], v[152:155], v[192:195], v[34:37]
	v_mfma_f32_16x16x32_bf16 v[22:25], v[144:147], v[200:203], v[22:25]
	v_mfma_f32_16x16x32_bf16 v[18:21], v[152:155], v[200:203], v[18:21]
	v_mfma_f32_16x16x32_bf16 v[62:65], v[148:151], v[180:183], v[62:65]
	v_mfma_f32_16x16x32_bf16 v[58:61], v[156:159], v[180:183], v[58:61]
	v_mfma_f32_16x16x32_bf16 v[54:57], v[148:151], v[188:191], v[54:57]
	v_mfma_f32_16x16x32_bf16 v[50:53], v[156:159], v[188:191], v[50:53]
	v_mfma_f32_16x16x32_bf16 v[38:41], v[148:151], v[196:199], v[38:41]
	v_mfma_f32_16x16x32_bf16 v[34:37], v[156:159], v[196:199], v[34:37]
	v_mfma_f32_16x16x32_bf16 v[22:25], v[148:151], v[204:207], v[22:25]
	v_mfma_f32_16x16x32_bf16 v[18:21], v[156:159], v[204:207], v[18:21]
	v_mfma_f32_16x16x32_bf16 v[46:49], v[160:163], v[176:179], v[46:49]
	v_mfma_f32_16x16x32_bf16 v[42:45], v[168:171], v[176:179], v[42:45]
	v_mfma_f32_16x16x32_bf16 v[30:33], v[160:163], v[184:187], v[30:33]
	v_mfma_f32_16x16x32_bf16 v[26:29], v[168:171], v[184:187], v[26:29]
	v_mfma_f32_16x16x32_bf16 v[14:17], v[160:163], v[192:195], v[14:17]
	v_mfma_f32_16x16x32_bf16 v[10:13], v[168:171], v[192:195], v[10:13]
	v_mfma_f32_16x16x32_bf16 v[6:9], v[160:163], v[200:203], v[6:9]
	v_mfma_f32_16x16x32_bf16 v[2:5], v[168:171], v[200:203], v[2:5]
	v_mfma_f32_16x16x32_bf16 v[46:49], v[164:167], v[180:183], v[46:49]
	v_mfma_f32_16x16x32_bf16 v[42:45], v[172:175], v[180:183], v[42:45]
	v_mfma_f32_16x16x32_bf16 v[30:33], v[164:167], v[188:191], v[30:33]
	v_mfma_f32_16x16x32_bf16 v[26:29], v[172:175], v[188:191], v[26:29]
	v_mfma_f32_16x16x32_bf16 v[14:17], v[164:167], v[196:199], v[14:17]
	v_mfma_f32_16x16x32_bf16 v[10:13], v[172:175], v[196:199], v[10:13]
	v_mfma_f32_16x16x32_bf16 v[6:9], v[164:167], v[204:207], v[6:9]
	v_mfma_f32_16x16x32_bf16 v[2:5], v[172:175], v[204:207], v[2:5]
	s_setprio 1
	s_barrier
	s_add_i32 s44, 0, 0x18000
	s_add_i32 s45, 0, 0x1c000
	v_add_u32_e32 v156, s44, v139
	v_add_u32_e32 v172, s45, v139
	ds_read_b128 v[144:147], v156
	ds_read_b128 v[148:151], v156 offset:1024
	ds_read_b128 v[152:155], v156 offset:2048
	ds_read_b128 v[156:159], v156 offset:3072
	ds_read_b128 v[160:163], v172
	ds_read_b128 v[164:167], v172 offset:1024
	ds_read_b128 v[168:171], v172 offset:2048
	ds_read_b128 v[172:175], v172 offset:3072
	s_add_u32 s26, s26, 0x40000
	s_addc_u32 s27, s27, 0
	s_mov_b32 m0, s31
	v_lshl_add_u64 v[216:217], s[26:27], 0, v[130:131]
	ds_read_b128 v[176:179], v143 offset:32768
	ds_read_b128 v[180:183], v143 offset:33792
	ds_read_b128 v[184:187], v143 offset:34816
	ds_read_b128 v[188:191], v143 offset:35840
	ds_read_b128 v[192:195], v143 offset:36864
	ds_read_b128 v[196:199], v143 offset:37888
	ds_read_b128 v[200:203], v143 offset:38912
	ds_read_b128 v[204:207], v143 offset:39936
	global_load_lds_dwordx4 v[216:217], off
	v_lshl_add_u64 v[216:217], s[26:27], 0, v[132:133]
	s_mov_b32 m0, s34
	s_nop 0
	global_load_lds_dwordx4 v[216:217], off
	s_waitcnt vmcnt(8)
	s_waitcnt lgkmcnt(0)
	s_barrier
	s_setprio 0
	s_waitcnt lgkmcnt(0)
	v_mfma_f32_16x16x32_bf16 v[126:129], v[144:147], v[176:179], v[126:129]
	v_mfma_f32_16x16x32_bf16 v[122:125], v[152:155], v[176:179], v[122:125]
	v_mfma_f32_16x16x32_bf16 v[118:121], v[144:147], v[184:187], v[118:121]
	v_mfma_f32_16x16x32_bf16 v[114:117], v[152:155], v[184:187], v[114:117]
	v_mfma_f32_16x16x32_bf16 v[106:109], v[144:147], v[192:195], v[106:109]
	v_mfma_f32_16x16x32_bf16 v[98:101], v[152:155], v[192:195], v[98:101]
	v_mfma_f32_16x16x32_bf16 v[90:93], v[144:147], v[200:203], v[90:93]
	v_mfma_f32_16x16x32_bf16 v[82:85], v[152:155], v[200:203], v[82:85]
	v_mfma_f32_16x16x32_bf16 v[126:129], v[148:151], v[180:183], v[126:129]
	v_mfma_f32_16x16x32_bf16 v[122:125], v[156:159], v[180:183], v[122:125]
	v_mfma_f32_16x16x32_bf16 v[118:121], v[148:151], v[188:191], v[118:121]
	v_mfma_f32_16x16x32_bf16 v[114:117], v[156:159], v[188:191], v[114:117]
	v_mfma_f32_16x16x32_bf16 v[106:109], v[148:151], v[196:199], v[106:109]
	v_mfma_f32_16x16x32_bf16 v[98:101], v[156:159], v[196:199], v[98:101]
	v_mfma_f32_16x16x32_bf16 v[90:93], v[148:151], v[204:207], v[90:93]
	v_mfma_f32_16x16x32_bf16 v[82:85], v[156:159], v[204:207], v[82:85]
	v_mfma_f32_16x16x32_bf16 v[110:113], v[160:163], v[176:179], v[110:113]
	v_mfma_f32_16x16x32_bf16 v[102:105], v[168:171], v[176:179], v[102:105]
	v_mfma_f32_16x16x32_bf16 v[94:97], v[160:163], v[184:187], v[94:97]
	v_mfma_f32_16x16x32_bf16 v[86:89], v[168:171], v[184:187], v[86:89]
	v_mfma_f32_16x16x32_bf16 v[78:81], v[160:163], v[192:195], v[78:81]
	v_mfma_f32_16x16x32_bf16 v[74:77], v[168:171], v[192:195], v[74:77]
	v_mfma_f32_16x16x32_bf16 v[70:73], v[160:163], v[200:203], v[70:73]
	v_mfma_f32_16x16x32_bf16 v[66:69], v[168:171], v[200:203], v[66:69]
	v_mfma_f32_16x16x32_bf16 v[110:113], v[164:167], v[180:183], v[110:113]
	v_mfma_f32_16x16x32_bf16 v[102:105], v[172:175], v[180:183], v[102:105]
	v_mfma_f32_16x16x32_bf16 v[94:97], v[164:167], v[188:191], v[94:97]
	v_mfma_f32_16x16x32_bf16 v[86:89], v[172:175], v[188:191], v[86:89]
	v_mfma_f32_16x16x32_bf16 v[78:81], v[164:167], v[196:199], v[78:81]
	v_mfma_f32_16x16x32_bf16 v[74:77], v[172:175], v[196:199], v[74:77]
	v_mfma_f32_16x16x32_bf16 v[70:73], v[164:167], v[204:207], v[70:73]
	v_mfma_f32_16x16x32_bf16 v[66:69], v[172:175], v[204:207], v[66:69]
	s_setprio 1
	s_barrier
	s_add_i32 s26, s44, s28
	v_lshl_add_u64 v[208:209], v[208:209], 0, s[6:7]
	s_mov_b32 m0, s26
	ds_read_b128 v[176:179], v143 offset:49152
	ds_read_b128 v[180:183], v143 offset:50176
	ds_read_b128 v[184:187], v143 offset:51200
	ds_read_b128 v[188:191], v143 offset:52224
	ds_read_b128 v[192:195], v143 offset:53248
	ds_read_b128 v[196:199], v143 offset:54272
	ds_read_b128 v[200:203], v143 offset:55296
	ds_read_b128 v[204:207], v143 offset:56320
	global_load_lds_dwordx4 v[208:209], off
	s_add_i32 m0, s26, 0x2000
	s_add_u32 s24, s24, 0x40080
	v_lshl_add_u64 v[208:209], v[210:211], 0, s[6:7]
	s_addc_u32 s25, s25, 0
	s_add_i32 s26, s45, s28
	global_load_lds_dwordx4 v[208:209], off
	v_lshl_add_u64 v[208:209], s[24:25], 0, v[130:131]
	s_mov_b32 m0, s26
	s_nop 0
	global_load_lds_dwordx4 v[208:209], off
	v_lshl_add_u64 v[208:209], s[24:25], 0, v[132:133]
	s_add_i32 m0, s26, 0x2000
	s_nop 0
	global_load_lds_dwordx4 v[208:209], off
	v_lshl_add_u64 v[208:209], v[212:213], 0, s[6:7]
	s_mov_b32 m0, s36
	s_nop 0
	global_load_lds_dwordx4 v[208:209], off
	v_lshl_add_u64 v[208:209], v[214:215], 0, s[6:7]
	s_mov_b32 m0, s37
	s_nop 0
	global_load_lds_dwordx4 v[208:209], off
	s_waitcnt vmcnt(8)
	s_waitcnt lgkmcnt(0)
	s_barrier
	s_setprio 0
	s_waitcnt lgkmcnt(0)
	v_mfma_f32_16x16x32_bf16 v[62:65], v[144:147], v[176:179], v[62:65]
	v_mfma_f32_16x16x32_bf16 v[58:61], v[152:155], v[176:179], v[58:61]
	v_mfma_f32_16x16x32_bf16 v[54:57], v[144:147], v[184:187], v[54:57]
	v_mfma_f32_16x16x32_bf16 v[50:53], v[152:155], v[184:187], v[50:53]
	v_mfma_f32_16x16x32_bf16 v[38:41], v[144:147], v[192:195], v[38:41]
	v_mfma_f32_16x16x32_bf16 v[34:37], v[152:155], v[192:195], v[34:37]
	v_mfma_f32_16x16x32_bf16 v[22:25], v[144:147], v[200:203], v[22:25]
	v_mfma_f32_16x16x32_bf16 v[18:21], v[152:155], v[200:203], v[18:21]
	v_mfma_f32_16x16x32_bf16 v[62:65], v[148:151], v[180:183], v[62:65]
	v_mfma_f32_16x16x32_bf16 v[58:61], v[156:159], v[180:183], v[58:61]
	v_mfma_f32_16x16x32_bf16 v[54:57], v[148:151], v[188:191], v[54:57]
	v_mfma_f32_16x16x32_bf16 v[50:53], v[156:159], v[188:191], v[50:53]
	v_mfma_f32_16x16x32_bf16 v[38:41], v[148:151], v[196:199], v[38:41]
	v_mfma_f32_16x16x32_bf16 v[34:37], v[156:159], v[196:199], v[34:37]
	v_mfma_f32_16x16x32_bf16 v[22:25], v[148:151], v[204:207], v[22:25]
	v_mfma_f32_16x16x32_bf16 v[18:21], v[156:159], v[204:207], v[18:21]
	v_mfma_f32_16x16x32_bf16 v[46:49], v[160:163], v[176:179], v[46:49]
	v_mfma_f32_16x16x32_bf16 v[42:45], v[168:171], v[176:179], v[42:45]
	v_mfma_f32_16x16x32_bf16 v[30:33], v[160:163], v[184:187], v[30:33]
	v_mfma_f32_16x16x32_bf16 v[26:29], v[168:171], v[184:187], v[26:29]
	v_mfma_f32_16x16x32_bf16 v[14:17], v[160:163], v[192:195], v[14:17]
	v_mfma_f32_16x16x32_bf16 v[10:13], v[168:171], v[192:195], v[10:13]
	v_mfma_f32_16x16x32_bf16 v[6:9], v[160:163], v[200:203], v[6:9]
	v_mfma_f32_16x16x32_bf16 v[2:5], v[168:171], v[200:203], v[2:5]
	v_mfma_f32_16x16x32_bf16 v[46:49], v[164:167], v[180:183], v[46:49]
	v_mfma_f32_16x16x32_bf16 v[42:45], v[172:175], v[180:183], v[42:45]
	v_mfma_f32_16x16x32_bf16 v[30:33], v[164:167], v[188:191], v[30:33]
	v_mfma_f32_16x16x32_bf16 v[26:29], v[172:175], v[188:191], v[26:29]
	v_mfma_f32_16x16x32_bf16 v[14:17], v[164:167], v[196:199], v[14:17]
	v_mfma_f32_16x16x32_bf16 v[10:13], v[172:175], v[196:199], v[10:13]
	v_mfma_f32_16x16x32_bf16 v[6:9], v[164:167], v[204:207], v[6:9]
	v_mfma_f32_16x16x32_bf16 v[2:5], v[172:175], v[204:207], v[2:5]
	s_setprio 1
	s_barrier
	s_add_i32 s43, s43, 2
	s_add_u32 s22, s22, 0x100
	s_addc_u32 s23, s23, 0
	s_add_u32 s41, s41, 0x100
	s_addc_u32 s42, s42, 0
	s_cmp_gt_u32 s43, 13
	s_cbranch_scc0 .LBB0_419
	s_and_b64 vcc, exec, s[8:9]
	s_cbranch_vccz .LBB0_422
	s_barrier

.LBB0_567:
	ds_read_b128 v[152:155], v149
	ds_read_b128 v[156:159], v149 offset:1024
	ds_read_b128 v[160:163], v149 offset:2048
	ds_read_b128 v[164:167], v149 offset:3072
	ds_read_b128 v[168:171], v150
	ds_read_b128 v[172:175], v150 offset:1024
	ds_read_b128 v[176:179], v150 offset:2048
	ds_read_b128 v[180:183], v150 offset:3072
	s_add_u32 s18, s16, 0x100
	s_addc_u32 s19, s17, 0
	s_cmp_eq_u32 s42, 2
	s_cselect_b32 s23, s7, s19
	s_cselect_b32 s22, s6, s18
	s_cselect_b32 s21, s15, s41
	s_cselect_b32 s20, s14, s40
	v_lshl_add_u64 v[216:217], s[16:17], 0, v[138:139]
	s_add_i32 m0, s11, 0xc000
	ds_read_b128 v[184:187], v151
	ds_read_b128 v[188:191], v151 offset:1024
	ds_read_b128 v[192:195], v151 offset:2048
	ds_read_b128 v[196:199], v151 offset:3072
	ds_read_b128 v[200:203], v151 offset:4096
	ds_read_b128 v[204:207], v151 offset:5120
	ds_read_b128 v[208:211], v151 offset:6144
	ds_read_b128 v[212:215], v151 offset:7168
	global_load_lds_dwordx4 v[216:217], off
	v_lshl_add_u64 v[216:217], s[16:17], 0, v[140:141]
	s_add_i32 m0, s11, 0xe000
	s_nop 0
	global_load_lds_dwordx4 v[216:217], off
	s_waitcnt vmcnt(8)
	s_waitcnt lgkmcnt(0)
	s_barrier
	s_setprio 0
	s_waitcnt lgkmcnt(0)
	v_mfma_f32_16x16x32_bf16 v[126:129], v[152:155], v[184:187], v[126:129]
	v_mfma_f32_16x16x32_bf16 v[122:125], v[160:163], v[184:187], v[122:125]
	v_mfma_f32_16x16x32_bf16 v[118:121], v[152:155], v[192:195], v[118:121]
	v_mfma_f32_16x16x32_bf16 v[114:117], v[160:163], v[192:195], v[114:117]
	v_mfma_f32_16x16x32_bf16 v[102:105], v[152:155], v[200:203], v[102:105]
	v_mfma_f32_16x16x32_bf16 v[98:101], v[160:163], v[200:203], v[98:101]
	v_mfma_f32_16x16x32_bf16 v[86:89], v[152:155], v[208:211], v[86:89]
	v_mfma_f32_16x16x32_bf16 v[82:85], v[160:163], v[208:211], v[82:85]
	v_mfma_f32_16x16x32_bf16 v[126:129], v[156:159], v[188:191], v[126:129]
	v_mfma_f32_16x16x32_bf16 v[122:125], v[164:167], v[188:191], v[122:125]
	v_mfma_f32_16x16x32_bf16 v[118:121], v[156:159], v[196:199], v[118:121]
	v_mfma_f32_16x16x32_bf16 v[114:117], v[164:167], v[196:199], v[114:117]
	v_mfma_f32_16x16x32_bf16 v[102:105], v[156:159], v[204:207], v[102:105]
	v_mfma_f32_16x16x32_bf16 v[98:101], v[164:167], v[204:207], v[98:101]
	v_mfma_f32_16x16x32_bf16 v[86:89], v[156:159], v[212:215], v[86:89]
	v_mfma_f32_16x16x32_bf16 v[82:85], v[164:167], v[212:215], v[82:85]
	v_mfma_f32_16x16x32_bf16 v[110:113], v[168:171], v[184:187], v[110:113]
	v_mfma_f32_16x16x32_bf16 v[106:109], v[176:179], v[184:187], v[106:109]
	v_mfma_f32_16x16x32_bf16 v[94:97], v[168:171], v[192:195], v[94:97]
	v_mfma_f32_16x16x32_bf16 v[90:93], v[176:179], v[192:195], v[90:93]
	v_mfma_f32_16x16x32_bf16 v[78:81], v[168:171], v[200:203], v[78:81]
	v_mfma_f32_16x16x32_bf16 v[74:77], v[176:179], v[200:203], v[74:77]
	v_mfma_f32_16x16x32_bf16 v[70:73], v[168:171], v[208:211], v[70:73]
	v_mfma_f32_16x16x32_bf16 v[66:69], v[176:179], v[208:211], v[66:69]
	v_mfma_f32_16x16x32_bf16 v[110:113], v[172:175], v[188:191], v[110:113]
	v_mfma_f32_16x16x32_bf16 v[106:109], v[180:183], v[188:191], v[106:109]
	v_mfma_f32_16x16x32_bf16 v[94:97], v[172:175], v[196:199], v[94:97]
	v_mfma_f32_16x16x32_bf16 v[90:93], v[180:183], v[196:199], v[90:93]
	v_mfma_f32_16x16x32_bf16 v[78:81], v[172:175], v[204:207], v[78:81]
	v_mfma_f32_16x16x32_bf16 v[74:77], v[180:183], v[204:207], v[74:77]
	v_mfma_f32_16x16x32_bf16 v[70:73], v[172:175], v[212:215], v[70:73]
	v_mfma_f32_16x16x32_bf16 v[66:69], v[180:183], v[212:215], v[66:69]
	s_setprio 1
	s_barrier
	s_add_i32 s16, s34, s2
	v_lshl_add_u64 v[216:217], s[20:21], 0, v[134:135]
	s_mov_b32 m0, s16
	ds_read_b128 v[184:187], v151 offset:16384
	ds_read_b128 v[188:191], v151 offset:17408
	ds_read_b128 v[192:195], v151 offset:18432
	ds_read_b128 v[196:199], v151 offset:19456
	ds_read_b128 v[200:203], v151 offset:20480
	ds_read_b128 v[204:207], v151 offset:21504
	ds_read_b128 v[208:211], v151 offset:22528
	ds_read_b128 v[212:215], v151 offset:23552
	global_load_lds_dwordx4 v[216:217], off
	s_add_i32 m0, s16, 0x2000
	s_add_u32 s16, s20, 0x18000
	v_lshl_add_u64 v[218:219], s[20:21], 0, v[130:131]
	s_addc_u32 s17, s21, 0
	s_add_i32 s43, s35, s2
	global_load_lds_dwordx4 v[218:219], off
	v_lshl_add_u64 v[220:221], s[16:17], 0, v[134:135]
	s_mov_b32 m0, s43
	v_lshl_add_u64 v[222:223], s[22:23], 0, v[132:133]
	global_load_lds_dwordx4 v[220:221], off
	v_lshl_add_u64 v[220:221], s[16:17], 0, v[130:131]
	s_add_i32 m0, s43, 0x2000
	s_nop 0
	global_load_lds_dwordx4 v[220:221], off
	v_lshl_add_u64 v[220:221], s[22:23], 0, v[136:137]
	s_mov_b32 m0, s11
	s_nop 0
	global_load_lds_dwordx4 v[220:221], off
	s_mov_b32 m0, s24
	s_nop 0
	global_load_lds_dwordx4 v[222:223], off
	s_waitcnt vmcnt(8)
	s_waitcnt lgkmcnt(0)
	s_barrier
	s_setprio 0
	s_waitcnt lgkmcnt(0)
	v_mfma_f32_16x16x32_bf16 v[62:65], v[152:155], v[184:187], v[62:65]
	v_mfma_f32_16x16x32_bf16 v[58:61], v[160:163], v[184:187], v[58:61]
	v_mfma_f32_16x16x32_bf16 v[54:57], v[152:155], v[192:195], v[54:57]
	v_mfma_f32_16x16x32_bf16 v[50:53], v[160:163], v[192:195], v[50:53]
	v_mfma_f32_16x16x32_bf16 v[38:41], v[152:155], v[200:203], v[38:41]
	v_mfma_f32_16x16x32_bf16 v[34:37], v[160:163], v[200:203], v[34:37]
	v_mfma_f32_16x16x32_bf16 v[22:25], v[152:155], v[208:211], v[22:25]
	v_mfma_f32_16x16x32_bf16 v[18:21], v[160:163], v[208:211], v[18:21]
	v_mfma_f32_16x16x32_bf16 v[62:65], v[156:159], v[188:191], v[62:65]
	v_mfma_f32_16x16x32_bf16 v[58:61], v[164:167], v[188:191], v[58:61]
	v_mfma_f32_16x16x32_bf16 v[54:57], v[156:159], v[196:199], v[54:57]
	v_mfma_f32_16x16x32_bf16 v[50:53], v[164:167], v[196:199], v[50:53]
	v_mfma_f32_16x16x32_bf16 v[38:41], v[156:159], v[204:207], v[38:41]
	v_mfma_f32_16x16x32_bf16 v[34:37], v[164:167], v[204:207], v[34:37]
	v_mfma_f32_16x16x32_bf16 v[22:25], v[156:159], v[212:215], v[22:25]
	v_mfma_f32_16x16x32_bf16 v[18:21], v[164:167], v[212:215], v[18:21]
	v_mfma_f32_16x16x32_bf16 v[46:49], v[168:171], v[184:187], v[46:49]
	v_mfma_f32_16x16x32_bf16 v[42:45], v[176:179], v[184:187], v[42:45]
	v_mfma_f32_16x16x32_bf16 v[30:33], v[168:171], v[192:195], v[30:33]
	v_mfma_f32_16x16x32_bf16 v[26:29], v[176:179], v[192:195], v[26:29]
	v_mfma_f32_16x16x32_bf16 v[14:17], v[168:171], v[200:203], v[14:17]
	v_mfma_f32_16x16x32_bf16 v[10:13], v[176:179], v[200:203], v[10:13]
	v_mfma_f32_16x16x32_bf16 v[6:9], v[168:171], v[208:211], v[6:9]
	v_mfma_f32_16x16x32_bf16 v[2:5], v[176:179], v[208:211], v[2:5]
	v_mfma_f32_16x16x32_bf16 v[46:49], v[172:175], v[188:191], v[46:49]
	v_mfma_f32_16x16x32_bf16 v[42:45], v[180:183], v[188:191], v[42:45]
	v_mfma_f32_16x16x32_bf16 v[30:33], v[172:175], v[196:199], v[30:33]
	v_mfma_f32_16x16x32_bf16 v[26:29], v[180:183], v[196:199], v[26:29]
	v_mfma_f32_16x16x32_bf16 v[14:17], v[172:175], v[204:207], v[14:17]
	v_mfma_f32_16x16x32_bf16 v[10:13], v[180:183], v[204:207], v[10:13]
	v_mfma_f32_16x16x32_bf16 v[6:9], v[172:175], v[212:215], v[6:9]
	v_mfma_f32_16x16x32_bf16 v[2:5], v[180:183], v[212:215], v[2:5]
	s_setprio 1
	s_barrier
	s_add_i32 s43, 0, 0x18000
	s_add_i32 s44, 0, 0x1c000
	v_add_u32_e32 v164, s43, v147
	v_add_u32_e32 v180, s44, v147
	ds_read_b128 v[152:155], v164
	ds_read_b128 v[156:159], v164 offset:1024
	ds_read_b128 v[160:163], v164 offset:2048
	ds_read_b128 v[164:167], v164 offset:3072
	ds_read_b128 v[168:171], v180
	ds_read_b128 v[172:175], v180 offset:1024
	ds_read_b128 v[176:179], v180 offset:2048
	ds_read_b128 v[180:183], v180 offset:3072
	s_add_u32 s16, s22, 0x18000
	s_addc_u32 s17, s23, 0
	s_mov_b32 m0, s25
	v_lshl_add_u64 v[224:225], s[16:17], 0, v[136:137]
	ds_read_b128 v[184:187], v151 offset:32768
	ds_read_b128 v[188:191], v151 offset:33792
	ds_read_b128 v[192:195], v151 offset:34816
	ds_read_b128 v[196:199], v151 offset:35840
	ds_read_b128 v[200:203], v151 offset:36864
	ds_read_b128 v[204:207], v151 offset:37888
	ds_read_b128 v[208:211], v151 offset:38912
	ds_read_b128 v[212:215], v151 offset:39936
	global_load_lds_dwordx4 v[224:225], off
	v_lshl_add_u64 v[224:225], s[16:17], 0, v[132:133]
	s_mov_b32 m0, s26
	s_nop 0
	global_load_lds_dwordx4 v[224:225], off
	s_waitcnt vmcnt(8)
	s_waitcnt lgkmcnt(0)
	s_barrier
	s_setprio 0
	s_waitcnt lgkmcnt(0)
	v_mfma_f32_16x16x32_bf16 v[126:129], v[152:155], v[184:187], v[126:129]
	v_mfma_f32_16x16x32_bf16 v[122:125], v[160:163], v[184:187], v[122:125]
	v_mfma_f32_16x16x32_bf16 v[118:121], v[152:155], v[192:195], v[118:121]
	v_mfma_f32_16x16x32_bf16 v[114:117], v[160:163], v[192:195], v[114:117]
	v_mfma_f32_16x16x32_bf16 v[102:105], v[152:155], v[200:203], v[102:105]
	v_mfma_f32_16x16x32_bf16 v[98:101], v[160:163], v[200:203], v[98:101]
	v_mfma_f32_16x16x32_bf16 v[86:89], v[152:155], v[208:211], v[86:89]
	v_mfma_f32_16x16x32_bf16 v[82:85], v[160:163], v[208:211], v[82:85]
	v_mfma_f32_16x16x32_bf16 v[126:129], v[156:159], v[188:191], v[126:129]
	v_mfma_f32_16x16x32_bf16 v[122:125], v[164:167], v[188:191], v[122:125]
	v_mfma_f32_16x16x32_bf16 v[118:121], v[156:159], v[196:199], v[118:121]
	v_mfma_f32_16x16x32_bf16 v[114:117], v[164:167], v[196:199], v[114:117]
	v_mfma_f32_16x16x32_bf16 v[102:105], v[156:159], v[204:207], v[102:105]
	v_mfma_f32_16x16x32_bf16 v[98:101], v[164:167], v[204:207], v[98:101]
	v_mfma_f32_16x16x32_bf16 v[86:89], v[156:159], v[212:215], v[86:89]
	v_mfma_f32_16x16x32_bf16 v[82:85], v[164:167], v[212:215], v[82:85]
	v_mfma_f32_16x16x32_bf16 v[110:113], v[168:171], v[184:187], v[110:113]
	v_mfma_f32_16x16x32_bf16 v[106:109], v[176:179], v[184:187], v[106:109]
	v_mfma_f32_16x16x32_bf16 v[94:97], v[168:171], v[192:195], v[94:97]
	v_mfma_f32_16x16x32_bf16 v[90:93], v[176:179], v[192:195], v[90:93]
	v_mfma_f32_16x16x32_bf16 v[78:81], v[168:171], v[200:203], v[78:81]
	v_mfma_f32_16x16x32_bf16 v[74:77], v[176:179], v[200:203], v[74:77]
	v_mfma_f32_16x16x32_bf16 v[70:73], v[168:171], v[208:211], v[70:73]
	v_mfma_f32_16x16x32_bf16 v[66:69], v[176:179], v[208:211], v[66:69]
	v_mfma_f32_16x16x32_bf16 v[110:113], v[172:175], v[188:191], v[110:113]
	v_mfma_f32_16x16x32_bf16 v[106:109], v[180:183], v[188:191], v[106:109]
	v_mfma_f32_16x16x32_bf16 v[94:97], v[172:175], v[196:199], v[94:97]
	v_mfma_f32_16x16x32_bf16 v[90:93], v[180:183], v[196:199], v[90:93]
	v_mfma_f32_16x16x32_bf16 v[78:81], v[172:175], v[204:207], v[78:81]
	v_mfma_f32_16x16x32_bf16 v[74:77], v[180:183], v[204:207], v[74:77]
	v_mfma_f32_16x16x32_bf16 v[70:73], v[172:175], v[212:215], v[70:73]
	v_mfma_f32_16x16x32_bf16 v[66:69], v[180:183], v[212:215], v[66:69]
	s_setprio 1
	s_barrier
	s_add_i32 s16, s43, s2
	v_lshl_add_u64 v[216:217], v[216:217], 0, s[8:9]
	s_mov_b32 m0, s16
	ds_read_b128 v[184:187], v151 offset:49152
	ds_read_b128 v[188:191], v151 offset:50176
	ds_read_b128 v[192:195], v151 offset:51200
	ds_read_b128 v[196:199], v151 offset:52224
	ds_read_b128 v[200:203], v151 offset:53248
	ds_read_b128 v[204:207], v151 offset:54272
	ds_read_b128 v[208:211], v151 offset:55296
	ds_read_b128 v[212:215], v151 offset:56320
	global_load_lds_dwordx4 v[216:217], off
	s_add_i32 m0, s16, 0x2000
	s_add_u32 s16, s20, 0x18080
	v_lshl_add_u64 v[216:217], v[218:219], 0, s[8:9]
	s_addc_u32 s17, s21, 0
	s_add_i32 s20, s44, s2
	global_load_lds_dwordx4 v[216:217], off
	v_lshl_add_u64 v[216:217], s[16:17], 0, v[134:135]
	s_mov_b32 m0, s20
	s_nop 0
	global_load_lds_dwordx4 v[216:217], off
	v_lshl_add_u64 v[216:217], s[16:17], 0, v[130:131]
	s_add_i32 m0, s20, 0x2000
	s_nop 0
	global_load_lds_dwordx4 v[216:217], off
	v_lshl_add_u64 v[216:217], v[220:221], 0, s[8:9]
	s_mov_b32 m0, s28
	s_nop 0
	global_load_lds_dwordx4 v[216:217], off
	v_lshl_add_u64 v[216:217], v[222:223], 0, s[8:9]
	s_mov_b32 m0, s29
	s_nop 0
	global_load_lds_dwordx4 v[216:217], off
	s_waitcnt vmcnt(8)
	s_waitcnt lgkmcnt(0)
	s_barrier
	s_setprio 0
	s_waitcnt lgkmcnt(0)
	v_mfma_f32_16x16x32_bf16 v[62:65], v[152:155], v[184:187], v[62:65]
	v_mfma_f32_16x16x32_bf16 v[58:61], v[160:163], v[184:187], v[58:61]
	v_mfma_f32_16x16x32_bf16 v[54:57], v[152:155], v[192:195], v[54:57]
	v_mfma_f32_16x16x32_bf16 v[50:53], v[160:163], v[192:195], v[50:53]
	v_mfma_f32_16x16x32_bf16 v[38:41], v[152:155], v[200:203], v[38:41]
	v_mfma_f32_16x16x32_bf16 v[34:37], v[160:163], v[200:203], v[34:37]
	v_mfma_f32_16x16x32_bf16 v[22:25], v[152:155], v[208:211], v[22:25]
	v_mfma_f32_16x16x32_bf16 v[18:21], v[160:163], v[208:211], v[18:21]
	v_mfma_f32_16x16x32_bf16 v[62:65], v[156:159], v[188:191], v[62:65]
	v_mfma_f32_16x16x32_bf16 v[58:61], v[164:167], v[188:191], v[58:61]
	v_mfma_f32_16x16x32_bf16 v[54:57], v[156:159], v[196:199], v[54:57]
	v_mfma_f32_16x16x32_bf16 v[50:53], v[164:167], v[196:199], v[50:53]
	v_mfma_f32_16x16x32_bf16 v[38:41], v[156:159], v[204:207], v[38:41]
	v_mfma_f32_16x16x32_bf16 v[34:37], v[164:167], v[204:207], v[34:37]
	v_mfma_f32_16x16x32_bf16 v[22:25], v[156:159], v[212:215], v[22:25]
	v_mfma_f32_16x16x32_bf16 v[18:21], v[164:167], v[212:215], v[18:21]
	v_mfma_f32_16x16x32_bf16 v[46:49], v[168:171], v[184:187], v[46:49]
	v_mfma_f32_16x16x32_bf16 v[42:45], v[176:179], v[184:187], v[42:45]
	v_mfma_f32_16x16x32_bf16 v[30:33], v[168:171], v[192:195], v[30:33]
	v_mfma_f32_16x16x32_bf16 v[26:29], v[176:179], v[192:195], v[26:29]
	v_mfma_f32_16x16x32_bf16 v[14:17], v[168:171], v[200:203], v[14:17]
	v_mfma_f32_16x16x32_bf16 v[10:13], v[176:179], v[200:203], v[10:13]
	v_mfma_f32_16x16x32_bf16 v[6:9], v[168:171], v[208:211], v[6:9]
	v_mfma_f32_16x16x32_bf16 v[2:5], v[176:179], v[208:211], v[2:5]
	v_mfma_f32_16x16x32_bf16 v[46:49], v[172:175], v[188:191], v[46:49]
	v_mfma_f32_16x16x32_bf16 v[42:45], v[180:183], v[188:191], v[42:45]
	v_mfma_f32_16x16x32_bf16 v[30:33], v[172:175], v[196:199], v[30:33]
	v_mfma_f32_16x16x32_bf16 v[26:29], v[180:183], v[196:199], v[26:29]
	v_mfma_f32_16x16x32_bf16 v[14:17], v[172:175], v[204:207], v[14:17]
	v_mfma_f32_16x16x32_bf16 v[10:13], v[180:183], v[204:207], v[10:13]
	v_mfma_f32_16x16x32_bf16 v[6:9], v[172:175], v[212:215], v[6:9]
	v_mfma_f32_16x16x32_bf16 v[2:5], v[180:183], v[212:215], v[2:5]
	s_setprio 1
	s_barrier
	s_add_i32 s42, s42, 2
	s_add_u32 s40, s40, 0x100
	s_addc_u32 s41, s41, 0
	s_cmp_gt_u32 s42, 3
	s_mov_b64 s[16:17], s[18:19]
	s_cbranch_scc0 .LBB0_567
	s_and_b64 vcc, exec, s[12:13]
	s_cbranch_vccz .LBB0_570
	s_barrier

.LBB0_583:
	s_add_u32 s31, s16, s30
	s_addc_u32 s47, s17, 0
	s_add_u32 s48, s31, 0x100
	s_addc_u32 s49, s47, 0
	s_and_b64 s[34:35], s[28:29], exec
	s_cselect_b32 s35, s21, s49
	s_cselect_b32 s34, s45, s48
	s_add_u32 s30, s14, s30
	s_addc_u32 s48, s15, 0
	s_add_u32 s30, s30, 0x100
	s_addc_u32 s48, s48, 0
	s_and_b64 s[28:29], s[28:29], exec
	s_cselect_b32 s53, s19, s48
	s_cselect_b32 s52, s46, s30
	s_add_u32 s56, s31, 0x10080
	ds_read_b128 v[148:151], v145
	ds_read_b128 v[152:155], v145 offset:1024
	ds_read_b128 v[156:159], v145 offset:2048
	ds_read_b128 v[160:163], v145 offset:3072
	ds_read_b128 v[164:167], v146
	ds_read_b128 v[168:171], v146 offset:1024
	ds_read_b128 v[172:175], v146 offset:2048
	ds_read_b128 v[176:179], v146 offset:3072
	s_addc_u32 s57, s47, 0
	s_add_i32 s72, s42, s2
	s_add_i32 m0, s11, 0xc000
	s_add_i32 s73, s11, 0xe000
	s_add_i32 s59, s72, 0x2000
	s_add_u32 s54, s52, 0x10000
	s_addc_u32 s55, s53, 0
	s_add_i32 s71, s43, s2
	s_add_i32 s70, s71, 0x2000
	s_add_i32 s58, 0, 0x18000
	s_add_i32 s51, 0, 0x1c000
	s_add_u32 s30, s34, 0x10000
	s_addc_u32 s31, s35, 0
	s_add_i32 s50, s58, s2
	s_add_i32 s48, s50, 0x2000
	s_add_u32 s28, s52, 0x10080
	s_addc_u32 s29, s53, 0
	s_add_i32 s49, s51, s2
	s_add_i32 s47, s49, 0x2000
	v_lshl_add_u64 v[212:213], s[56:57], 0, v[136:137]
	ds_read_b128 v[180:183], v147
	ds_read_b128 v[184:187], v147 offset:1024
	ds_read_b128 v[188:191], v147 offset:2048
	ds_read_b128 v[192:195], v147 offset:3072
	ds_read_b128 v[196:199], v147 offset:4096
	ds_read_b128 v[200:203], v147 offset:5120
	ds_read_b128 v[204:207], v147 offset:6144
	ds_read_b128 v[208:211], v147 offset:7168
	global_load_lds_dwordx4 v[212:213], off
	v_lshl_add_u64 v[212:213], s[56:57], 0, v[132:133]
	s_mov_b32 m0, s73
	s_nop 0
	global_load_lds_dwordx4 v[212:213], off
	s_waitcnt vmcnt(8)
	s_waitcnt lgkmcnt(0)
	s_barrier
	s_setprio 0
	s_waitcnt lgkmcnt(0)
	v_mfma_f32_16x16x32_bf16 v[126:129], v[148:151], v[180:183], v[126:129]
	v_mfma_f32_16x16x32_bf16 v[122:125], v[156:159], v[180:183], v[122:125]
	v_mfma_f32_16x16x32_bf16 v[118:121], v[148:151], v[188:191], v[118:121]
	v_mfma_f32_16x16x32_bf16 v[114:117], v[156:159], v[188:191], v[114:117]
	v_mfma_f32_16x16x32_bf16 v[102:105], v[148:151], v[196:199], v[102:105]
	v_mfma_f32_16x16x32_bf16 v[98:101], v[156:159], v[196:199], v[98:101]
	v_mfma_f32_16x16x32_bf16 v[86:89], v[148:151], v[204:207], v[86:89]
	v_mfma_f32_16x16x32_bf16 v[82:85], v[156:159], v[204:207], v[82:85]
	v_mfma_f32_16x16x32_bf16 v[126:129], v[152:155], v[184:187], v[126:129]
	v_mfma_f32_16x16x32_bf16 v[122:125], v[160:163], v[184:187], v[122:125]
	v_mfma_f32_16x16x32_bf16 v[118:121], v[152:155], v[192:195], v[118:121]
	v_mfma_f32_16x16x32_bf16 v[114:117], v[160:163], v[192:195], v[114:117]
	v_mfma_f32_16x16x32_bf16 v[102:105], v[152:155], v[200:203], v[102:105]
	v_mfma_f32_16x16x32_bf16 v[98:101], v[160:163], v[200:203], v[98:101]
	v_mfma_f32_16x16x32_bf16 v[86:89], v[152:155], v[208:211], v[86:89]
	v_mfma_f32_16x16x32_bf16 v[82:85], v[160:163], v[208:211], v[82:85]
	v_mfma_f32_16x16x32_bf16 v[110:113], v[164:167], v[180:183], v[110:113]
	v_mfma_f32_16x16x32_bf16 v[106:109], v[172:175], v[180:183], v[106:109]
	v_mfma_f32_16x16x32_bf16 v[94:97], v[164:167], v[188:191], v[94:97]
	v_mfma_f32_16x16x32_bf16 v[90:93], v[172:175], v[188:191], v[90:93]
	v_mfma_f32_16x16x32_bf16 v[78:81], v[164:167], v[196:199], v[78:81]
	v_mfma_f32_16x16x32_bf16 v[74:77], v[172:175], v[196:199], v[74:77]
	v_mfma_f32_16x16x32_bf16 v[70:73], v[164:167], v[204:207], v[70:73]
	v_mfma_f32_16x16x32_bf16 v[66:69], v[172:175], v[204:207], v[66:69]
	v_mfma_f32_16x16x32_bf16 v[110:113], v[168:171], v[184:187], v[110:113]
	v_mfma_f32_16x16x32_bf16 v[106:109], v[176:179], v[184:187], v[106:109]
	v_mfma_f32_16x16x32_bf16 v[94:97], v[168:171], v[192:195], v[94:97]
	v_mfma_f32_16x16x32_bf16 v[90:93], v[176:179], v[192:195], v[90:93]
	v_mfma_f32_16x16x32_bf16 v[78:81], v[168:171], v[200:203], v[78:81]
	v_mfma_f32_16x16x32_bf16 v[74:77], v[176:179], v[200:203], v[74:77]
	v_mfma_f32_16x16x32_bf16 v[70:73], v[168:171], v[208:211], v[70:73]
	v_mfma_f32_16x16x32_bf16 v[66:69], v[176:179], v[208:211], v[66:69]
	s_setprio 1
	s_barrier
	s_mov_b32 m0, s72
	v_lshl_add_u64 v[212:213], s[52:53], 0, v[134:135]
	ds_read_b128 v[180:183], v147 offset:16384
	ds_read_b128 v[184:187], v147 offset:17408
	ds_read_b128 v[188:191], v147 offset:18432
	ds_read_b128 v[192:195], v147 offset:19456
	ds_read_b128 v[196:199], v147 offset:20480
	ds_read_b128 v[200:203], v147 offset:21504
	ds_read_b128 v[204:207], v147 offset:22528
	ds_read_b128 v[208:211], v147 offset:23552
	global_load_lds_dwordx4 v[212:213], off
	v_lshl_add_u64 v[214:215], s[52:53], 0, v[130:131]
	s_mov_b32 m0, s59
	v_lshl_add_u64 v[216:217], s[54:55], 0, v[134:135]
	global_load_lds_dwordx4 v[214:215], off
	s_mov_b32 m0, s71
	v_lshl_add_u64 v[218:219], s[34:35], 0, v[132:133]
	global_load_lds_dwordx4 v[216:217], off
	v_lshl_add_u64 v[216:217], s[54:55], 0, v[130:131]
	s_mov_b32 m0, s70
	s_nop 0
	global_load_lds_dwordx4 v[216:217], off
	v_lshl_add_u64 v[216:217], s[34:35], 0, v[136:137]
	s_mov_b32 m0, s11
	s_nop 0
	global_load_lds_dwordx4 v[216:217], off
	s_mov_b32 m0, s13
	s_nop 0
	global_load_lds_dwordx4 v[218:219], off
	s_waitcnt vmcnt(8)
	s_waitcnt lgkmcnt(0)
	s_barrier
	s_setprio 0
	s_waitcnt lgkmcnt(0)
	v_mfma_f32_16x16x32_bf16 v[62:65], v[148:151], v[180:183], v[62:65]
	v_mfma_f32_16x16x32_bf16 v[58:61], v[156:159], v[180:183], v[58:61]
	v_mfma_f32_16x16x32_bf16 v[54:57], v[148:151], v[188:191], v[54:57]
	v_mfma_f32_16x16x32_bf16 v[50:53], v[156:159], v[188:191], v[50:53]
	v_mfma_f32_16x16x32_bf16 v[38:41], v[148:151], v[196:199], v[38:41]
	v_mfma_f32_16x16x32_bf16 v[34:37], v[156:159], v[196:199], v[34:37]
	v_mfma_f32_16x16x32_bf16 v[22:25], v[148:151], v[204:207], v[22:25]
	v_mfma_f32_16x16x32_bf16 v[18:21], v[156:159], v[204:207], v[18:21]
	v_mfma_f32_16x16x32_bf16 v[62:65], v[152:155], v[184:187], v[62:65]
	v_mfma_f32_16x16x32_bf16 v[58:61], v[160:163], v[184:187], v[58:61]
	v_mfma_f32_16x16x32_bf16 v[54:57], v[152:155], v[192:195], v[54:57]
	v_mfma_f32_16x16x32_bf16 v[50:53], v[160:163], v[192:195], v[50:53]
	v_mfma_f32_16x16x32_bf16 v[38:41], v[152:155], v[200:203], v[38:41]
	v_mfma_f32_16x16x32_bf16 v[34:37], v[160:163], v[200:203], v[34:37]
	v_mfma_f32_16x16x32_bf16 v[22:25], v[152:155], v[208:211], v[22:25]
	v_mfma_f32_16x16x32_bf16 v[18:21], v[160:163], v[208:211], v[18:21]
	v_mfma_f32_16x16x32_bf16 v[46:49], v[164:167], v[180:183], v[46:49]
	v_mfma_f32_16x16x32_bf16 v[42:45], v[172:175], v[180:183], v[42:45]
	v_mfma_f32_16x16x32_bf16 v[30:33], v[164:167], v[188:191], v[30:33]
	v_mfma_f32_16x16x32_bf16 v[26:29], v[172:175], v[188:191], v[26:29]
	v_mfma_f32_16x16x32_bf16 v[14:17], v[164:167], v[196:199], v[14:17]
	v_mfma_f32_16x16x32_bf16 v[10:13], v[172:175], v[196:199], v[10:13]
	v_mfma_f32_16x16x32_bf16 v[6:9], v[164:167], v[204:207], v[6:9]
	v_mfma_f32_16x16x32_bf16 v[2:5], v[172:175], v[204:207], v[2:5]
	v_mfma_f32_16x16x32_bf16 v[46:49], v[168:171], v[184:187], v[46:49]
	v_mfma_f32_16x16x32_bf16 v[42:45], v[176:179], v[184:187], v[42:45]
	v_mfma_f32_16x16x32_bf16 v[30:33], v[168:171], v[192:195], v[30:33]
	v_mfma_f32_16x16x32_bf16 v[26:29], v[176:179], v[192:195], v[26:29]
	v_mfma_f32_16x16x32_bf16 v[14:17], v[168:171], v[200:203], v[14:17]
	v_mfma_f32_16x16x32_bf16 v[10:13], v[176:179], v[200:203], v[10:13]
	v_mfma_f32_16x16x32_bf16 v[6:9], v[168:171], v[208:211], v[6:9]
	v_mfma_f32_16x16x32_bf16 v[2:5], v[176:179], v[208:211], v[2:5]
	s_setprio 1
	s_barrier
	v_add_u32_e32 v160, s58, v143
	v_add_u32_e32 v176, s51, v143
	ds_read_b128 v[148:151], v160
	ds_read_b128 v[152:155], v160 offset:1024
	ds_read_b128 v[156:159], v160 offset:2048
	ds_read_b128 v[160:163], v160 offset:3072
	ds_read_b128 v[164:167], v176
	ds_read_b128 v[168:171], v176 offset:1024
	ds_read_b128 v[172:175], v176 offset:2048
	ds_read_b128 v[176:179], v176 offset:3072
	s_mov_b32 m0, s36
	v_lshl_add_u64 v[220:221], s[30:31], 0, v[136:137]
	ds_read_b128 v[180:183], v147 offset:32768
	ds_read_b128 v[184:187], v147 offset:33792
	ds_read_b128 v[188:191], v147 offset:34816
	ds_read_b128 v[192:195], v147 offset:35840
	ds_read_b128 v[196:199], v147 offset:36864
	ds_read_b128 v[200:203], v147 offset:37888
	ds_read_b128 v[204:207], v147 offset:38912
	ds_read_b128 v[208:211], v147 offset:39936
	global_load_lds_dwordx4 v[220:221], off
	v_lshl_add_u64 v[220:221], s[30:31], 0, v[132:133]
	s_mov_b32 m0, s37
	s_nop 0
	global_load_lds_dwordx4 v[220:221], off
	s_waitcnt vmcnt(8)
	s_waitcnt lgkmcnt(0)
	s_barrier
	s_setprio 0
	s_waitcnt lgkmcnt(0)
	v_mfma_f32_16x16x32_bf16 v[126:129], v[148:151], v[180:183], v[126:129]
	v_mfma_f32_16x16x32_bf16 v[122:125], v[156:159], v[180:183], v[122:125]
	v_mfma_f32_16x16x32_bf16 v[118:121], v[148:151], v[188:191], v[118:121]
	v_mfma_f32_16x16x32_bf16 v[114:117], v[156:159], v[188:191], v[114:117]
	v_mfma_f32_16x16x32_bf16 v[102:105], v[148:151], v[196:199], v[102:105]
	v_mfma_f32_16x16x32_bf16 v[98:101], v[156:159], v[196:199], v[98:101]
	v_mfma_f32_16x16x32_bf16 v[86:89], v[148:151], v[204:207], v[86:89]
	v_mfma_f32_16x16x32_bf16 v[82:85], v[156:159], v[204:207], v[82:85]
	v_mfma_f32_16x16x32_bf16 v[126:129], v[152:155], v[184:187], v[126:129]
	v_mfma_f32_16x16x32_bf16 v[122:125], v[160:163], v[184:187], v[122:125]
	v_mfma_f32_16x16x32_bf16 v[118:121], v[152:155], v[192:195], v[118:121]
	v_mfma_f32_16x16x32_bf16 v[114:117], v[160:163], v[192:195], v[114:117]
	v_mfma_f32_16x16x32_bf16 v[102:105], v[152:155], v[200:203], v[102:105]
	v_mfma_f32_16x16x32_bf16 v[98:101], v[160:163], v[200:203], v[98:101]
	v_mfma_f32_16x16x32_bf16 v[86:89], v[152:155], v[208:211], v[86:89]
	v_mfma_f32_16x16x32_bf16 v[82:85], v[160:163], v[208:211], v[82:85]
	v_mfma_f32_16x16x32_bf16 v[110:113], v[164:167], v[180:183], v[110:113]
	v_mfma_f32_16x16x32_bf16 v[106:109], v[172:175], v[180:183], v[106:109]
	v_mfma_f32_16x16x32_bf16 v[94:97], v[164:167], v[188:191], v[94:97]
	v_mfma_f32_16x16x32_bf16 v[90:93], v[172:175], v[188:191], v[90:93]
	v_mfma_f32_16x16x32_bf16 v[78:81], v[164:167], v[196:199], v[78:81]
	v_mfma_f32_16x16x32_bf16 v[74:77], v[172:175], v[196:199], v[74:77]
	v_mfma_f32_16x16x32_bf16 v[70:73], v[164:167], v[204:207], v[70:73]
	v_mfma_f32_16x16x32_bf16 v[66:69], v[172:175], v[204:207], v[66:69]
	v_mfma_f32_16x16x32_bf16 v[110:113], v[168:171], v[184:187], v[110:113]
	v_mfma_f32_16x16x32_bf16 v[106:109], v[176:179], v[184:187], v[106:109]
	v_mfma_f32_16x16x32_bf16 v[94:97], v[168:171], v[192:195], v[94:97]
	v_mfma_f32_16x16x32_bf16 v[90:93], v[176:179], v[192:195], v[90:93]
	v_mfma_f32_16x16x32_bf16 v[78:81], v[168:171], v[200:203], v[78:81]
	v_mfma_f32_16x16x32_bf16 v[74:77], v[176:179], v[200:203], v[74:77]
	v_mfma_f32_16x16x32_bf16 v[70:73], v[168:171], v[208:211], v[70:73]
	v_mfma_f32_16x16x32_bf16 v[66:69], v[176:179], v[208:211], v[66:69]
	s_setprio 1
	s_barrier
	s_mov_b32 m0, s50
	v_lshl_add_u64 v[212:213], v[212:213], 0, s[6:7]
	ds_read_b128 v[180:183], v147 offset:49152
	ds_read_b128 v[184:187], v147 offset:50176
	ds_read_b128 v[188:191], v147 offset:51200
	ds_read_b128 v[192:195], v147 offset:52224
	ds_read_b128 v[196:199], v147 offset:53248
	ds_read_b128 v[200:203], v147 offset:54272
	ds_read_b128 v[204:207], v147 offset:55296
	ds_read_b128 v[208:211], v147 offset:56320
	global_load_lds_dwordx4 v[212:213], off
	v_lshl_add_u64 v[212:213], v[214:215], 0, s[6:7]
	s_mov_b32 m0, s48
	s_nop 0
	global_load_lds_dwordx4 v[212:213], off
	v_lshl_add_u64 v[212:213], s[28:29], 0, v[134:135]
	s_mov_b32 m0, s49
	s_nop 0
	global_load_lds_dwordx4 v[212:213], off
	v_lshl_add_u64 v[212:213], s[28:29], 0, v[130:131]
	s_mov_b32 m0, s47
	s_nop 0
	global_load_lds_dwordx4 v[212:213], off
	v_lshl_add_u64 v[212:213], v[216:217], 0, s[6:7]
	s_mov_b32 m0, s39
	s_nop 0
	global_load_lds_dwordx4 v[212:213], off
	v_lshl_add_u64 v[212:213], v[218:219], 0, s[6:7]
	s_mov_b32 m0, s40
	s_nop 0
	global_load_lds_dwordx4 v[212:213], off
	s_waitcnt vmcnt(8)
	s_waitcnt lgkmcnt(0)
	s_barrier
	s_setprio 0
	s_waitcnt lgkmcnt(0)
	v_mfma_f32_16x16x32_bf16 v[62:65], v[148:151], v[180:183], v[62:65]
	v_mfma_f32_16x16x32_bf16 v[58:61], v[156:159], v[180:183], v[58:61]
	v_mfma_f32_16x16x32_bf16 v[54:57], v[148:151], v[188:191], v[54:57]
	v_mfma_f32_16x16x32_bf16 v[50:53], v[156:159], v[188:191], v[50:53]
	v_mfma_f32_16x16x32_bf16 v[38:41], v[148:151], v[196:199], v[38:41]
	v_mfma_f32_16x16x32_bf16 v[34:37], v[156:159], v[196:199], v[34:37]
	v_mfma_f32_16x16x32_bf16 v[22:25], v[148:151], v[204:207], v[22:25]
	v_mfma_f32_16x16x32_bf16 v[18:21], v[156:159], v[204:207], v[18:21]
	v_mfma_f32_16x16x32_bf16 v[62:65], v[152:155], v[184:187], v[62:65]
	v_mfma_f32_16x16x32_bf16 v[58:61], v[160:163], v[184:187], v[58:61]
	v_mfma_f32_16x16x32_bf16 v[54:57], v[152:155], v[192:195], v[54:57]
	v_mfma_f32_16x16x32_bf16 v[50:53], v[160:163], v[192:195], v[50:53]
	v_mfma_f32_16x16x32_bf16 v[38:41], v[152:155], v[200:203], v[38:41]
	v_mfma_f32_16x16x32_bf16 v[34:37], v[160:163], v[200:203], v[34:37]
	v_mfma_f32_16x16x32_bf16 v[22:25], v[152:155], v[208:211], v[22:25]
	v_mfma_f32_16x16x32_bf16 v[18:21], v[160:163], v[208:211], v[18:21]
	v_mfma_f32_16x16x32_bf16 v[46:49], v[164:167], v[180:183], v[46:49]
	v_mfma_f32_16x16x32_bf16 v[42:45], v[172:175], v[180:183], v[42:45]
	v_mfma_f32_16x16x32_bf16 v[30:33], v[164:167], v[188:191], v[30:33]
	v_mfma_f32_16x16x32_bf16 v[26:29], v[172:175], v[188:191], v[26:29]
	v_mfma_f32_16x16x32_bf16 v[14:17], v[164:167], v[196:199], v[14:17]
	v_mfma_f32_16x16x32_bf16 v[10:13], v[172:175], v[196:199], v[10:13]
	v_mfma_f32_16x16x32_bf16 v[6:9], v[164:167], v[204:207], v[6:9]
	v_mfma_f32_16x16x32_bf16 v[2:5], v[172:175], v[204:207], v[2:5]
	v_mfma_f32_16x16x32_bf16 v[46:49], v[168:171], v[184:187], v[46:49]
	v_mfma_f32_16x16x32_bf16 v[42:45], v[176:179], v[184:187], v[42:45]
	v_mfma_f32_16x16x32_bf16 v[30:33], v[168:171], v[192:195], v[30:33]
	v_mfma_f32_16x16x32_bf16 v[26:29], v[176:179], v[192:195], v[26:29]
	v_mfma_f32_16x16x32_bf16 v[14:17], v[168:171], v[200:203], v[14:17]
	v_mfma_f32_16x16x32_bf16 v[10:13], v[176:179], v[200:203], v[10:13]
	v_mfma_f32_16x16x32_bf16 v[6:9], v[168:171], v[208:211], v[6:9]
	v_mfma_f32_16x16x32_bf16 v[2:5], v[176:179], v[208:211], v[2:5]
	s_setprio 1
	s_barrier
	s_movk_i32 s30, 0x100
	s_andn2_b64 vcc, exec, s[26:27]
	s_mov_b64 s[28:29], -1
	s_mov_b64 s[26:27], 0
	s_cbranch_vccz .LBB0_583
	s_and_b64 vcc, exec, s[8:9]
	s_cbranch_vccz .LBB0_586
	s_barrier

.LBB0_1033:
	ds_read_b128 v[146:149], v161
	ds_read_b128 v[150:153], v161 offset:1024
	ds_read_b128 v[154:157], v161 offset:2048
	ds_read_b128 v[164:167], v161 offset:3072
	ds_read_b128 v[168:171], v162
	ds_read_b128 v[172:175], v162 offset:1024
	ds_read_b128 v[176:179], v162 offset:2048
	ds_read_b128 v[180:183], v162 offset:3072
	s_add_u32 s28, s26, 0xfffc0080
	s_addc_u32 s29, s27, -1
	s_cmp_eq_u32 s43, 12
	s_cselect_b32 s31, s10, s29
	s_cselect_b32 s30, s11, s28
	s_cselect_b32 s29, s15, s42
	s_cselect_b32 s28, s17, s23
	v_lshl_add_u64 v[218:219], s[26:27], 0, v[138:139]
	s_add_i32 m0, s25, 0xc000
	ds_read_b128 v[184:187], v163
	ds_read_b128 v[188:191], v163 offset:1024
	ds_read_b128 v[192:195], v163 offset:2048
	ds_read_b128 v[196:199], v163 offset:3072
	ds_read_b128 v[202:205], v163 offset:4096
	ds_read_b128 v[206:209], v163 offset:5120
	ds_read_b128 v[210:213], v163 offset:6144
	ds_read_b128 v[214:217], v163 offset:7168
	global_load_lds_dwordx4 v[218:219], off
	v_lshl_add_u64 v[218:219], s[26:27], 0, v[140:141]
	s_add_i32 m0, s25, 0xe000
	s_nop 0
	global_load_lds_dwordx4 v[218:219], off
	s_waitcnt vmcnt(8)
	s_waitcnt lgkmcnt(0)
	s_barrier
	s_setprio 0
	s_waitcnt lgkmcnt(0)
	v_mfma_f32_16x16x32_bf16 v[126:129], v[146:149], v[184:187], v[126:129]
	v_mfma_f32_16x16x32_bf16 v[122:125], v[154:157], v[184:187], v[122:125]
	v_mfma_f32_16x16x32_bf16 v[118:121], v[146:149], v[192:195], v[118:121]
	v_mfma_f32_16x16x32_bf16 v[106:109], v[154:157], v[192:195], v[106:109]
	v_mfma_f32_16x16x32_bf16 v[102:105], v[146:149], v[202:205], v[102:105]
	v_mfma_f32_16x16x32_bf16 v[94:97], v[154:157], v[202:205], v[94:97]
	v_mfma_f32_16x16x32_bf16 v[86:89], v[146:149], v[210:213], v[86:89]
	v_mfma_f32_16x16x32_bf16 v[78:81], v[154:157], v[210:213], v[78:81]
	v_mfma_f32_16x16x32_bf16 v[126:129], v[150:153], v[188:191], v[126:129]
	v_mfma_f32_16x16x32_bf16 v[122:125], v[164:167], v[188:191], v[122:125]
	v_mfma_f32_16x16x32_bf16 v[118:121], v[150:153], v[196:199], v[118:121]
	v_mfma_f32_16x16x32_bf16 v[106:109], v[164:167], v[196:199], v[106:109]
	v_mfma_f32_16x16x32_bf16 v[102:105], v[150:153], v[206:209], v[102:105]
	v_mfma_f32_16x16x32_bf16 v[94:97], v[164:167], v[206:209], v[94:97]
	v_mfma_f32_16x16x32_bf16 v[86:89], v[150:153], v[214:217], v[86:89]
	v_mfma_f32_16x16x32_bf16 v[78:81], v[164:167], v[214:217], v[78:81]
	v_mfma_f32_16x16x32_bf16 v[114:117], v[168:171], v[184:187], v[114:117]
	v_mfma_f32_16x16x32_bf16 v[110:113], v[176:179], v[184:187], v[110:113]
	v_mfma_f32_16x16x32_bf16 v[98:101], v[168:171], v[192:195], v[98:101]
	v_mfma_f32_16x16x32_bf16 v[90:93], v[176:179], v[192:195], v[90:93]
	v_mfma_f32_16x16x32_bf16 v[82:85], v[168:171], v[202:205], v[82:85]
	v_mfma_f32_16x16x32_bf16 v[74:77], v[176:179], v[202:205], v[74:77]
	v_mfma_f32_16x16x32_bf16 v[70:73], v[168:171], v[210:213], v[70:73]
	v_mfma_f32_16x16x32_bf16 v[66:69], v[176:179], v[210:213], v[66:69]
	v_mfma_f32_16x16x32_bf16 v[114:117], v[172:175], v[188:191], v[114:117]
	v_mfma_f32_16x16x32_bf16 v[110:113], v[180:183], v[188:191], v[110:113]
	v_mfma_f32_16x16x32_bf16 v[98:101], v[172:175], v[196:199], v[98:101]
	v_mfma_f32_16x16x32_bf16 v[90:93], v[180:183], v[196:199], v[90:93]
	v_mfma_f32_16x16x32_bf16 v[82:85], v[172:175], v[206:209], v[82:85]
	v_mfma_f32_16x16x32_bf16 v[74:77], v[180:183], v[206:209], v[74:77]
	v_mfma_f32_16x16x32_bf16 v[70:73], v[172:175], v[214:217], v[70:73]
	v_mfma_f32_16x16x32_bf16 v[66:69], v[180:183], v[214:217], v[66:69]
	s_setprio 1
	s_barrier
	s_add_i32 s44, s80, s34
	v_lshl_add_u64 v[218:219], s[28:29], 0, v[132:133]
	s_mov_b32 m0, s44
	ds_read_b128 v[184:187], v163 offset:16384
	ds_read_b128 v[188:191], v163 offset:17408
	ds_read_b128 v[192:195], v163 offset:18432
	ds_read_b128 v[196:199], v163 offset:19456
	ds_read_b128 v[202:205], v163 offset:20480
	ds_read_b128 v[206:209], v163 offset:21504
	ds_read_b128 v[210:213], v163 offset:22528
	ds_read_b128 v[214:217], v163 offset:23552
	global_load_lds_dwordx4 v[218:219], off
	s_add_i32 m0, s44, 0x2000
	s_add_u32 s44, s28, 0x40000
	v_lshl_add_u64 v[220:221], s[28:29], 0, v[136:137]
	s_addc_u32 s45, s29, 0
	s_add_i32 s52, s51, s34
	global_load_lds_dwordx4 v[220:221], off
	v_lshl_add_u64 v[222:223], s[44:45], 0, v[132:133]
	s_mov_b32 m0, s52
	v_lshl_add_u64 v[224:225], s[30:31], 0, v[134:135]
	global_load_lds_dwordx4 v[222:223], off
	v_lshl_add_u64 v[222:223], s[44:45], 0, v[136:137]
	s_add_i32 m0, s52, 0x2000
	s_nop 0
	global_load_lds_dwordx4 v[222:223], off
	v_lshl_add_u64 v[222:223], s[30:31], 0, v[130:131]
	s_mov_b32 m0, s25
	s_nop 0
	global_load_lds_dwordx4 v[222:223], off
	s_mov_b32 m0, s35
	s_nop 0
	global_load_lds_dwordx4 v[224:225], off
	s_waitcnt vmcnt(8)
	s_waitcnt lgkmcnt(0)
	s_barrier
	s_setprio 0
	s_waitcnt lgkmcnt(0)
	v_mfma_f32_16x16x32_bf16 v[62:65], v[146:149], v[184:187], v[62:65]
	v_mfma_f32_16x16x32_bf16 v[58:61], v[154:157], v[184:187], v[58:61]
	v_mfma_f32_16x16x32_bf16 v[54:57], v[146:149], v[192:195], v[54:57]
	v_mfma_f32_16x16x32_bf16 v[50:53], v[154:157], v[192:195], v[50:53]
	v_mfma_f32_16x16x32_bf16 v[34:37], v[146:149], v[202:205], v[34:37]
	v_mfma_f32_16x16x32_bf16 v[30:33], v[154:157], v[202:205], v[30:33]
	v_mfma_f32_16x16x32_bf16 v[22:25], v[146:149], v[210:213], v[22:25]
	v_mfma_f32_16x16x32_bf16 v[14:17], v[154:157], v[210:213], v[14:17]
	v_mfma_f32_16x16x32_bf16 v[62:65], v[150:153], v[188:191], v[62:65]
	v_mfma_f32_16x16x32_bf16 v[58:61], v[164:167], v[188:191], v[58:61]
	v_mfma_f32_16x16x32_bf16 v[54:57], v[150:153], v[196:199], v[54:57]
	v_mfma_f32_16x16x32_bf16 v[50:53], v[164:167], v[196:199], v[50:53]
	v_mfma_f32_16x16x32_bf16 v[34:37], v[150:153], v[206:209], v[34:37]
	v_mfma_f32_16x16x32_bf16 v[30:33], v[164:167], v[206:209], v[30:33]
	v_mfma_f32_16x16x32_bf16 v[22:25], v[150:153], v[214:217], v[22:25]
	v_mfma_f32_16x16x32_bf16 v[14:17], v[164:167], v[214:217], v[14:17]
	v_mfma_f32_16x16x32_bf16 v[46:49], v[168:171], v[184:187], v[46:49]
	v_mfma_f32_16x16x32_bf16 v[42:45], v[176:179], v[184:187], v[42:45]
	v_mfma_f32_16x16x32_bf16 v[38:41], v[168:171], v[192:195], v[38:41]
	v_mfma_f32_16x16x32_bf16 v[26:29], v[176:179], v[192:195], v[26:29]
	v_mfma_f32_16x16x32_bf16 v[18:21], v[168:171], v[202:205], v[18:21]
	v_mfma_f32_16x16x32_bf16 v[10:13], v[176:179], v[202:205], v[10:13]
	v_mfma_f32_16x16x32_bf16 v[6:9], v[168:171], v[210:213], v[6:9]
	v_mfma_f32_16x16x32_bf16 v[2:5], v[176:179], v[210:213], v[2:5]
	v_mfma_f32_16x16x32_bf16 v[46:49], v[172:175], v[188:191], v[46:49]
	v_mfma_f32_16x16x32_bf16 v[42:45], v[180:183], v[188:191], v[42:45]
	v_mfma_f32_16x16x32_bf16 v[38:41], v[172:175], v[196:199], v[38:41]
	v_mfma_f32_16x16x32_bf16 v[26:29], v[180:183], v[196:199], v[26:29]
	v_mfma_f32_16x16x32_bf16 v[18:21], v[172:175], v[206:209], v[18:21]
	v_mfma_f32_16x16x32_bf16 v[10:13], v[180:183], v[206:209], v[10:13]
	v_mfma_f32_16x16x32_bf16 v[6:9], v[172:175], v[214:217], v[6:9]
	v_mfma_f32_16x16x32_bf16 v[2:5], v[180:183], v[214:217], v[2:5]
	s_setprio 1
	s_barrier
	s_add_i32 s44, 0, 0x18000
	s_add_i32 s45, 0, 0x1c000
	v_add_u32_e32 v164, s44, v159
	v_add_u32_e32 v180, s45, v159
	ds_read_b128 v[146:149], v164
	ds_read_b128 v[150:153], v164 offset:1024
	ds_read_b128 v[154:157], v164 offset:2048
	ds_read_b128 v[164:167], v164 offset:3072
	ds_read_b128 v[168:171], v180
	ds_read_b128 v[172:175], v180 offset:1024
	ds_read_b128 v[176:179], v180 offset:2048
	ds_read_b128 v[180:183], v180 offset:3072
	s_add_u32 s30, s30, 0x40000
	s_addc_u32 s31, s31, 0
	s_mov_b32 m0, s36
	v_lshl_add_u64 v[226:227], s[30:31], 0, v[130:131]
	ds_read_b128 v[184:187], v163 offset:32768
	ds_read_b128 v[188:191], v163 offset:33792
	ds_read_b128 v[192:195], v163 offset:34816
	ds_read_b128 v[196:199], v163 offset:35840
	ds_read_b128 v[202:205], v163 offset:36864
	ds_read_b128 v[206:209], v163 offset:37888
	ds_read_b128 v[210:213], v163 offset:38912
	ds_read_b128 v[214:217], v163 offset:39936
	global_load_lds_dwordx4 v[226:227], off
	v_lshl_add_u64 v[226:227], s[30:31], 0, v[134:135]
	s_mov_b32 m0, s37
	s_nop 0
	global_load_lds_dwordx4 v[226:227], off
	s_waitcnt vmcnt(8)
	s_waitcnt lgkmcnt(0)
	s_barrier
	s_setprio 0
	s_waitcnt lgkmcnt(0)
	v_mfma_f32_16x16x32_bf16 v[126:129], v[146:149], v[184:187], v[126:129]
	v_mfma_f32_16x16x32_bf16 v[122:125], v[154:157], v[184:187], v[122:125]
	v_mfma_f32_16x16x32_bf16 v[118:121], v[146:149], v[192:195], v[118:121]
	v_mfma_f32_16x16x32_bf16 v[106:109], v[154:157], v[192:195], v[106:109]
	v_mfma_f32_16x16x32_bf16 v[102:105], v[146:149], v[202:205], v[102:105]
	v_mfma_f32_16x16x32_bf16 v[94:97], v[154:157], v[202:205], v[94:97]
	v_mfma_f32_16x16x32_bf16 v[86:89], v[146:149], v[210:213], v[86:89]
	v_mfma_f32_16x16x32_bf16 v[78:81], v[154:157], v[210:213], v[78:81]
	v_mfma_f32_16x16x32_bf16 v[126:129], v[150:153], v[188:191], v[126:129]
	v_mfma_f32_16x16x32_bf16 v[122:125], v[164:167], v[188:191], v[122:125]
	v_mfma_f32_16x16x32_bf16 v[118:121], v[150:153], v[196:199], v[118:121]
	v_mfma_f32_16x16x32_bf16 v[106:109], v[164:167], v[196:199], v[106:109]
	v_mfma_f32_16x16x32_bf16 v[102:105], v[150:153], v[206:209], v[102:105]
	v_mfma_f32_16x16x32_bf16 v[94:97], v[164:167], v[206:209], v[94:97]
	v_mfma_f32_16x16x32_bf16 v[86:89], v[150:153], v[214:217], v[86:89]
	v_mfma_f32_16x16x32_bf16 v[78:81], v[164:167], v[214:217], v[78:81]
	v_mfma_f32_16x16x32_bf16 v[114:117], v[168:171], v[184:187], v[114:117]
	v_mfma_f32_16x16x32_bf16 v[110:113], v[176:179], v[184:187], v[110:113]
	v_mfma_f32_16x16x32_bf16 v[98:101], v[168:171], v[192:195], v[98:101]
	v_mfma_f32_16x16x32_bf16 v[90:93], v[176:179], v[192:195], v[90:93]
	v_mfma_f32_16x16x32_bf16 v[82:85], v[168:171], v[202:205], v[82:85]
	v_mfma_f32_16x16x32_bf16 v[74:77], v[176:179], v[202:205], v[74:77]
	v_mfma_f32_16x16x32_bf16 v[70:73], v[168:171], v[210:213], v[70:73]
	v_mfma_f32_16x16x32_bf16 v[66:69], v[176:179], v[210:213], v[66:69]
	v_mfma_f32_16x16x32_bf16 v[114:117], v[172:175], v[188:191], v[114:117]
	v_mfma_f32_16x16x32_bf16 v[110:113], v[180:183], v[188:191], v[110:113]
	v_mfma_f32_16x16x32_bf16 v[98:101], v[172:175], v[196:199], v[98:101]
	v_mfma_f32_16x16x32_bf16 v[90:93], v[180:183], v[196:199], v[90:93]
	v_mfma_f32_16x16x32_bf16 v[82:85], v[172:175], v[206:209], v[82:85]
	v_mfma_f32_16x16x32_bf16 v[74:77], v[180:183], v[206:209], v[74:77]
	v_mfma_f32_16x16x32_bf16 v[70:73], v[172:175], v[214:217], v[70:73]
	v_mfma_f32_16x16x32_bf16 v[66:69], v[180:183], v[214:217], v[66:69]
	s_setprio 1
	s_barrier
	s_add_i32 s30, s44, s34
	v_lshl_add_u64 v[218:219], v[218:219], 0, s[4:5]
	s_mov_b32 m0, s30
	ds_read_b128 v[184:187], v163 offset:49152
	ds_read_b128 v[188:191], v163 offset:50176
	ds_read_b128 v[192:195], v163 offset:51200
	ds_read_b128 v[196:199], v163 offset:52224
	ds_read_b128 v[202:205], v163 offset:53248
	ds_read_b128 v[206:209], v163 offset:54272
	ds_read_b128 v[210:213], v163 offset:55296
	ds_read_b128 v[214:217], v163 offset:56320
	global_load_lds_dwordx4 v[218:219], off
	s_add_i32 m0, s30, 0x2000
	s_add_u32 s28, s28, 0x40080
	v_lshl_add_u64 v[218:219], v[220:221], 0, s[4:5]
	s_addc_u32 s29, s29, 0
	s_add_i32 s30, s45, s34
	global_load_lds_dwordx4 v[218:219], off
	v_lshl_add_u64 v[218:219], s[28:29], 0, v[132:133]
	s_mov_b32 m0, s30
	s_nop 0
	global_load_lds_dwordx4 v[218:219], off
	v_lshl_add_u64 v[218:219], s[28:29], 0, v[136:137]
	s_add_i32 m0, s30, 0x2000
	s_nop 0
	global_load_lds_dwordx4 v[218:219], off
	v_lshl_add_u64 v[218:219], v[222:223], 0, s[4:5]
	s_mov_b32 m0, s39
	s_nop 0
	global_load_lds_dwordx4 v[218:219], off
	v_lshl_add_u64 v[218:219], v[224:225], 0, s[4:5]
	s_mov_b32 m0, s40
	s_nop 0
	global_load_lds_dwordx4 v[218:219], off
	s_waitcnt vmcnt(8)
	s_waitcnt lgkmcnt(0)
	s_barrier
	s_setprio 0
	s_waitcnt lgkmcnt(0)
	v_mfma_f32_16x16x32_bf16 v[62:65], v[146:149], v[184:187], v[62:65]
	v_mfma_f32_16x16x32_bf16 v[58:61], v[154:157], v[184:187], v[58:61]
	v_mfma_f32_16x16x32_bf16 v[54:57], v[146:149], v[192:195], v[54:57]
	v_mfma_f32_16x16x32_bf16 v[50:53], v[154:157], v[192:195], v[50:53]
	v_mfma_f32_16x16x32_bf16 v[34:37], v[146:149], v[202:205], v[34:37]
	v_mfma_f32_16x16x32_bf16 v[30:33], v[154:157], v[202:205], v[30:33]
	v_mfma_f32_16x16x32_bf16 v[22:25], v[146:149], v[210:213], v[22:25]
	v_mfma_f32_16x16x32_bf16 v[14:17], v[154:157], v[210:213], v[14:17]
	v_mfma_f32_16x16x32_bf16 v[62:65], v[150:153], v[188:191], v[62:65]
	v_mfma_f32_16x16x32_bf16 v[58:61], v[164:167], v[188:191], v[58:61]
	v_mfma_f32_16x16x32_bf16 v[54:57], v[150:153], v[196:199], v[54:57]
	v_mfma_f32_16x16x32_bf16 v[50:53], v[164:167], v[196:199], v[50:53]
	v_mfma_f32_16x16x32_bf16 v[34:37], v[150:153], v[206:209], v[34:37]
	v_mfma_f32_16x16x32_bf16 v[30:33], v[164:167], v[206:209], v[30:33]
	v_mfma_f32_16x16x32_bf16 v[22:25], v[150:153], v[214:217], v[22:25]
	v_mfma_f32_16x16x32_bf16 v[14:17], v[164:167], v[214:217], v[14:17]
	v_mfma_f32_16x16x32_bf16 v[46:49], v[168:171], v[184:187], v[46:49]
	v_mfma_f32_16x16x32_bf16 v[42:45], v[176:179], v[184:187], v[42:45]
	v_mfma_f32_16x16x32_bf16 v[38:41], v[168:171], v[192:195], v[38:41]
	v_mfma_f32_16x16x32_bf16 v[26:29], v[176:179], v[192:195], v[26:29]
	v_mfma_f32_16x16x32_bf16 v[18:21], v[168:171], v[202:205], v[18:21]
	v_mfma_f32_16x16x32_bf16 v[10:13], v[176:179], v[202:205], v[10:13]
	v_mfma_f32_16x16x32_bf16 v[6:9], v[168:171], v[210:213], v[6:9]
	v_mfma_f32_16x16x32_bf16 v[2:5], v[176:179], v[210:213], v[2:5]
	v_mfma_f32_16x16x32_bf16 v[46:49], v[172:175], v[188:191], v[46:49]
	v_mfma_f32_16x16x32_bf16 v[42:45], v[180:183], v[188:191], v[42:45]
	v_mfma_f32_16x16x32_bf16 v[38:41], v[172:175], v[196:199], v[38:41]
	v_mfma_f32_16x16x32_bf16 v[26:29], v[180:183], v[196:199], v[26:29]
	v_mfma_f32_16x16x32_bf16 v[18:21], v[172:175], v[206:209], v[18:21]
	v_mfma_f32_16x16x32_bf16 v[10:13], v[180:183], v[206:209], v[10:13]
	v_mfma_f32_16x16x32_bf16 v[6:9], v[172:175], v[214:217], v[6:9]
	v_mfma_f32_16x16x32_bf16 v[2:5], v[180:183], v[214:217], v[2:5]
	s_setprio 1
	s_barrier
	s_add_i32 s43, s43, 2
	s_add_u32 s26, s26, 0x100
	s_addc_u32 s27, s27, 0
	s_add_u32 s23, s23, 0x100
	s_addc_u32 s42, s42, 0
	s_cmp_gt_u32 s43, 13
	s_cbranch_scc0 .LBB0_1033
	v_readlane_b32 s60, v255, 1
	s_and_b64 vcc, exec, s[12:13]
	v_readlane_b32 s66, v255, 7
	v_readlane_b32 s67, v255, 8
	v_readlane_b32 s61, v255, 2
	v_readlane_b32 s62, v255, 3
	v_readlane_b32 s63, v255, 4
	v_readlane_b32 s64, v255, 5
	v_readlane_b32 s65, v255, 6
	v_readlane_b32 s68, v255, 9
	v_readlane_b32 s69, v255, 10
	v_readlane_b32 s70, v255, 11
	v_readlane_b32 s71, v255, 12
	v_readlane_b32 s72, v255, 13
	v_readlane_b32 s73, v255, 14
	v_readlane_b32 s74, v255, 15
	v_readlane_b32 s75, v255, 16
	s_cbranch_vccz .LBB0_1036
	s_barrier

.LBB0_1134:
	ds_read_b128 v[148:151], v169
	ds_read_b128 v[152:155], v169 offset:1024
	ds_read_b128 v[156:159], v169 offset:2048
	ds_read_b128 v[160:163], v169 offset:3072
	ds_read_b128 v[172:175], v170
	ds_read_b128 v[176:179], v170 offset:1024
	ds_read_b128 v[180:183], v170 offset:2048
	ds_read_b128 v[184:187], v170 offset:3072
	s_add_u32 s30, s12, 0xfffc0080
	s_addc_u32 s31, s13, -1
	s_cmp_eq_u32 s48, 12
	s_cselect_b32 s35, s3, s31
	s_cselect_b32 s34, s10, s30
	s_cselect_b32 s31, s11, s47
	s_cselect_b32 s30, s23, s25
	v_lshl_add_u64 v[222:223], s[12:13], 0, v[140:141]
	s_add_i32 m0, s36, 0xc000
	ds_read_b128 v[188:191], v171
	ds_read_b128 v[192:195], v171 offset:1024
	ds_read_b128 v[196:199], v171 offset:2048
	ds_read_b128 v[202:205], v171 offset:3072
	ds_read_b128 v[206:209], v171 offset:4096
	ds_read_b128 v[210:213], v171 offset:5120
	ds_read_b128 v[214:217], v171 offset:6144
	ds_read_b128 v[218:221], v171 offset:7168
	global_load_lds_dwordx4 v[222:223], off
	v_lshl_add_u64 v[222:223], s[12:13], 0, v[142:143]
	s_add_i32 m0, s36, 0xe000
	s_nop 0
	global_load_lds_dwordx4 v[222:223], off
	s_waitcnt vmcnt(8)
	s_waitcnt lgkmcnt(0)
	s_barrier
	s_setprio 0
	s_waitcnt lgkmcnt(0)
	v_mfma_f32_16x16x32_bf16 v[126:129], v[148:151], v[188:191], v[126:129]
	v_mfma_f32_16x16x32_bf16 v[122:125], v[156:159], v[188:191], v[122:125]
	v_mfma_f32_16x16x32_bf16 v[118:121], v[148:151], v[196:199], v[118:121]
	v_mfma_f32_16x16x32_bf16 v[110:113], v[156:159], v[196:199], v[110:113]
	v_mfma_f32_16x16x32_bf16 v[102:105], v[148:151], v[206:209], v[102:105]
	v_mfma_f32_16x16x32_bf16 v[94:97], v[156:159], v[206:209], v[94:97]
	v_mfma_f32_16x16x32_bf16 v[86:89], v[148:151], v[214:217], v[86:89]
	v_mfma_f32_16x16x32_bf16 v[78:81], v[156:159], v[214:217], v[78:81]
	v_mfma_f32_16x16x32_bf16 v[126:129], v[152:155], v[192:195], v[126:129]
	v_mfma_f32_16x16x32_bf16 v[122:125], v[160:163], v[192:195], v[122:125]
	v_mfma_f32_16x16x32_bf16 v[118:121], v[152:155], v[202:205], v[118:121]
	v_mfma_f32_16x16x32_bf16 v[110:113], v[160:163], v[202:205], v[110:113]
	v_mfma_f32_16x16x32_bf16 v[102:105], v[152:155], v[210:213], v[102:105]
	v_mfma_f32_16x16x32_bf16 v[94:97], v[160:163], v[210:213], v[94:97]
	v_mfma_f32_16x16x32_bf16 v[86:89], v[152:155], v[218:221], v[86:89]
	v_mfma_f32_16x16x32_bf16 v[78:81], v[160:163], v[218:221], v[78:81]
	v_mfma_f32_16x16x32_bf16 v[114:117], v[172:175], v[188:191], v[114:117]
	v_mfma_f32_16x16x32_bf16 v[106:109], v[180:183], v[188:191], v[106:109]
	v_mfma_f32_16x16x32_bf16 v[98:101], v[172:175], v[196:199], v[98:101]
	v_mfma_f32_16x16x32_bf16 v[90:93], v[180:183], v[196:199], v[90:93]
	v_mfma_f32_16x16x32_bf16 v[82:85], v[172:175], v[206:209], v[82:85]
	v_mfma_f32_16x16x32_bf16 v[74:77], v[180:183], v[206:209], v[74:77]
	v_mfma_f32_16x16x32_bf16 v[70:73], v[172:175], v[214:217], v[70:73]
	v_mfma_f32_16x16x32_bf16 v[66:69], v[180:183], v[214:217], v[66:69]
	v_mfma_f32_16x16x32_bf16 v[114:117], v[176:179], v[192:195], v[114:117]
	v_mfma_f32_16x16x32_bf16 v[106:109], v[184:187], v[192:195], v[106:109]
	v_mfma_f32_16x16x32_bf16 v[98:101], v[176:179], v[202:205], v[98:101]
	v_mfma_f32_16x16x32_bf16 v[90:93], v[184:187], v[202:205], v[90:93]
	v_mfma_f32_16x16x32_bf16 v[82:85], v[176:179], v[210:213], v[82:85]
	v_mfma_f32_16x16x32_bf16 v[74:77], v[184:187], v[210:213], v[74:77]
	v_mfma_f32_16x16x32_bf16 v[70:73], v[176:179], v[218:221], v[70:73]
	v_mfma_f32_16x16x32_bf16 v[66:69], v[184:187], v[218:221], v[66:69]
	s_setprio 1
	s_barrier
	s_add_i32 s49, s80, s21
	v_lshl_add_u64 v[222:223], s[30:31], 0, v[132:133]
	s_mov_b32 m0, s49
	ds_read_b128 v[188:191], v171 offset:16384
	ds_read_b128 v[192:195], v171 offset:17408
	ds_read_b128 v[196:199], v171 offset:18432
	ds_read_b128 v[202:205], v171 offset:19456
	ds_read_b128 v[206:209], v171 offset:20480
	ds_read_b128 v[210:213], v171 offset:21504
	ds_read_b128 v[214:217], v171 offset:22528
	ds_read_b128 v[218:221], v171 offset:23552
	global_load_lds_dwordx4 v[222:223], off
	s_add_i32 m0, s49, 0x2000
	s_add_u32 s50, s30, 0x40000
	v_lshl_add_u64 v[224:225], s[30:31], 0, v[136:137]
	s_addc_u32 s51, s31, 0
	s_add_i32 s49, s44, s21
	global_load_lds_dwordx4 v[224:225], off
	v_lshl_add_u64 v[226:227], s[50:51], 0, v[132:133]
	s_mov_b32 m0, s49
	v_lshl_add_u64 v[228:229], s[34:35], 0, v[134:135]
	global_load_lds_dwordx4 v[226:227], off
	v_lshl_add_u64 v[226:227], s[50:51], 0, v[136:137]
	s_add_i32 m0, s49, 0x2000
	s_nop 0
	global_load_lds_dwordx4 v[226:227], off
	v_lshl_add_u64 v[226:227], s[34:35], 0, v[130:131]
	s_mov_b32 m0, s36
	s_nop 0
	global_load_lds_dwordx4 v[226:227], off
	s_mov_b32 m0, s37
	s_nop 0
	global_load_lds_dwordx4 v[228:229], off
	s_waitcnt vmcnt(8)
	s_waitcnt lgkmcnt(0)
	s_barrier
	s_setprio 0
	s_waitcnt lgkmcnt(0)
	v_mfma_f32_16x16x32_bf16 v[62:65], v[148:151], v[188:191], v[62:65]
	v_mfma_f32_16x16x32_bf16 v[58:61], v[156:159], v[188:191], v[58:61]
	v_mfma_f32_16x16x32_bf16 v[54:57], v[148:151], v[196:199], v[54:57]
	v_mfma_f32_16x16x32_bf16 v[46:49], v[156:159], v[196:199], v[46:49]
	v_mfma_f32_16x16x32_bf16 v[38:41], v[148:151], v[206:209], v[38:41]
	v_mfma_f32_16x16x32_bf16 v[30:33], v[156:159], v[206:209], v[30:33]
	v_mfma_f32_16x16x32_bf16 v[22:25], v[148:151], v[214:217], v[22:25]
	v_mfma_f32_16x16x32_bf16 v[14:17], v[156:159], v[214:217], v[14:17]
	v_mfma_f32_16x16x32_bf16 v[62:65], v[152:155], v[192:195], v[62:65]
	v_mfma_f32_16x16x32_bf16 v[58:61], v[160:163], v[192:195], v[58:61]
	v_mfma_f32_16x16x32_bf16 v[54:57], v[152:155], v[202:205], v[54:57]
	v_mfma_f32_16x16x32_bf16 v[46:49], v[160:163], v[202:205], v[46:49]
	v_mfma_f32_16x16x32_bf16 v[38:41], v[152:155], v[210:213], v[38:41]
	v_mfma_f32_16x16x32_bf16 v[30:33], v[160:163], v[210:213], v[30:33]
	v_mfma_f32_16x16x32_bf16 v[22:25], v[152:155], v[218:221], v[22:25]
	v_mfma_f32_16x16x32_bf16 v[14:17], v[160:163], v[218:221], v[14:17]
	v_mfma_f32_16x16x32_bf16 v[50:53], v[172:175], v[188:191], v[50:53]
	v_mfma_f32_16x16x32_bf16 v[42:45], v[180:183], v[188:191], v[42:45]
	v_mfma_f32_16x16x32_bf16 v[34:37], v[172:175], v[196:199], v[34:37]
	v_mfma_f32_16x16x32_bf16 v[26:29], v[180:183], v[196:199], v[26:29]
	v_mfma_f32_16x16x32_bf16 v[18:21], v[172:175], v[206:209], v[18:21]
	v_mfma_f32_16x16x32_bf16 v[10:13], v[180:183], v[206:209], v[10:13]
	v_mfma_f32_16x16x32_bf16 v[6:9], v[172:175], v[214:217], v[6:9]
	v_mfma_f32_16x16x32_bf16 v[2:5], v[180:183], v[214:217], v[2:5]
	v_mfma_f32_16x16x32_bf16 v[50:53], v[176:179], v[192:195], v[50:53]
	v_mfma_f32_16x16x32_bf16 v[42:45], v[184:187], v[192:195], v[42:45]
	v_mfma_f32_16x16x32_bf16 v[34:37], v[176:179], v[202:205], v[34:37]
	v_mfma_f32_16x16x32_bf16 v[26:29], v[184:187], v[202:205], v[26:29]
	v_mfma_f32_16x16x32_bf16 v[18:21], v[176:179], v[210:213], v[18:21]
	v_mfma_f32_16x16x32_bf16 v[10:13], v[184:187], v[210:213], v[10:13]
	v_mfma_f32_16x16x32_bf16 v[6:9], v[176:179], v[218:221], v[6:9]
	v_mfma_f32_16x16x32_bf16 v[2:5], v[184:187], v[218:221], v[2:5]
	s_setprio 1
	s_barrier
	s_add_i32 s49, 0, 0x18000
	s_add_i32 s50, 0, 0x1c000
	v_add_u32_e32 v160, s49, v167
	v_add_u32_e32 v164, s50, v167
	ds_read_b128 v[148:151], v160
	ds_read_b128 v[152:155], v160 offset:1024
	ds_read_b128 v[156:159], v160 offset:2048
	ds_read_b128 v[160:163], v160 offset:3072
	ds_read_b128 v[172:175], v164
	ds_read_b128 v[176:179], v164 offset:1024
	ds_read_b128 v[180:183], v164 offset:2048
	ds_read_b128 v[184:187], v164 offset:3072
	s_add_u32 s34, s34, 0x40000
	s_addc_u32 s35, s35, 0
	s_mov_b32 m0, s38
	v_lshl_add_u64 v[230:231], s[34:35], 0, v[130:131]
	ds_read_b128 v[188:191], v171 offset:32768
	ds_read_b128 v[192:195], v171 offset:33792
	ds_read_b128 v[196:199], v171 offset:34816
	ds_read_b128 v[202:205], v171 offset:35840
	ds_read_b128 v[206:209], v171 offset:36864
	ds_read_b128 v[210:213], v171 offset:37888
	ds_read_b128 v[214:217], v171 offset:38912
	ds_read_b128 v[218:221], v171 offset:39936
	global_load_lds_dwordx4 v[230:231], off
	v_lshl_add_u64 v[230:231], s[34:35], 0, v[134:135]
	s_mov_b32 m0, s39
	s_nop 0
	global_load_lds_dwordx4 v[230:231], off
	s_waitcnt vmcnt(8)
	s_waitcnt lgkmcnt(0)
	s_barrier
	s_setprio 0
	s_waitcnt lgkmcnt(0)
	v_mfma_f32_16x16x32_bf16 v[126:129], v[148:151], v[188:191], v[126:129]
	v_mfma_f32_16x16x32_bf16 v[122:125], v[156:159], v[188:191], v[122:125]
	v_mfma_f32_16x16x32_bf16 v[118:121], v[148:151], v[196:199], v[118:121]
	v_mfma_f32_16x16x32_bf16 v[110:113], v[156:159], v[196:199], v[110:113]
	v_mfma_f32_16x16x32_bf16 v[102:105], v[148:151], v[206:209], v[102:105]
	v_mfma_f32_16x16x32_bf16 v[94:97], v[156:159], v[206:209], v[94:97]
	v_mfma_f32_16x16x32_bf16 v[86:89], v[148:151], v[214:217], v[86:89]
	v_mfma_f32_16x16x32_bf16 v[78:81], v[156:159], v[214:217], v[78:81]
	v_mfma_f32_16x16x32_bf16 v[126:129], v[152:155], v[192:195], v[126:129]
	v_mfma_f32_16x16x32_bf16 v[122:125], v[160:163], v[192:195], v[122:125]
	v_mfma_f32_16x16x32_bf16 v[118:121], v[152:155], v[202:205], v[118:121]
	v_mfma_f32_16x16x32_bf16 v[110:113], v[160:163], v[202:205], v[110:113]
	v_mfma_f32_16x16x32_bf16 v[102:105], v[152:155], v[210:213], v[102:105]
	v_mfma_f32_16x16x32_bf16 v[94:97], v[160:163], v[210:213], v[94:97]
	v_mfma_f32_16x16x32_bf16 v[86:89], v[152:155], v[218:221], v[86:89]
	v_mfma_f32_16x16x32_bf16 v[78:81], v[160:163], v[218:221], v[78:81]
	v_mfma_f32_16x16x32_bf16 v[114:117], v[172:175], v[188:191], v[114:117]
	v_mfma_f32_16x16x32_bf16 v[106:109], v[180:183], v[188:191], v[106:109]
	v_mfma_f32_16x16x32_bf16 v[98:101], v[172:175], v[196:199], v[98:101]
	v_mfma_f32_16x16x32_bf16 v[90:93], v[180:183], v[196:199], v[90:93]
	v_mfma_f32_16x16x32_bf16 v[82:85], v[172:175], v[206:209], v[82:85]
	v_mfma_f32_16x16x32_bf16 v[74:77], v[180:183], v[206:209], v[74:77]
	v_mfma_f32_16x16x32_bf16 v[70:73], v[172:175], v[214:217], v[70:73]
	v_mfma_f32_16x16x32_bf16 v[66:69], v[180:183], v[214:217], v[66:69]
	v_mfma_f32_16x16x32_bf16 v[114:117], v[176:179], v[192:195], v[114:117]
	v_mfma_f32_16x16x32_bf16 v[106:109], v[184:187], v[192:195], v[106:109]
	v_mfma_f32_16x16x32_bf16 v[98:101], v[176:179], v[202:205], v[98:101]
	v_mfma_f32_16x16x32_bf16 v[90:93], v[184:187], v[202:205], v[90:93]
	v_mfma_f32_16x16x32_bf16 v[82:85], v[176:179], v[210:213], v[82:85]
	v_mfma_f32_16x16x32_bf16 v[74:77], v[184:187], v[210:213], v[74:77]
	v_mfma_f32_16x16x32_bf16 v[70:73], v[176:179], v[218:221], v[70:73]
	v_mfma_f32_16x16x32_bf16 v[66:69], v[184:187], v[218:221], v[66:69]
	s_setprio 1
	s_barrier
	s_add_i32 s34, s49, s21
	v_lshl_add_u64 v[222:223], v[222:223], 0, s[14:15]
	s_mov_b32 m0, s34
	ds_read_b128 v[188:191], v171 offset:49152
	ds_read_b128 v[192:195], v171 offset:50176
	ds_read_b128 v[196:199], v171 offset:51200
	ds_read_b128 v[202:205], v171 offset:52224
	ds_read_b128 v[206:209], v171 offset:53248
	ds_read_b128 v[210:213], v171 offset:54272
	ds_read_b128 v[214:217], v171 offset:55296
	ds_read_b128 v[218:221], v171 offset:56320
	global_load_lds_dwordx4 v[222:223], off
	s_add_i32 m0, s34, 0x2000
	s_add_u32 s30, s30, 0x40080
	v_lshl_add_u64 v[222:223], v[224:225], 0, s[14:15]
	s_addc_u32 s31, s31, 0
	s_add_i32 s34, s50, s21
	global_load_lds_dwordx4 v[222:223], off
	v_lshl_add_u64 v[222:223], s[30:31], 0, v[132:133]
	s_mov_b32 m0, s34
	s_nop 0
	global_load_lds_dwordx4 v[222:223], off
	v_lshl_add_u64 v[222:223], s[30:31], 0, v[136:137]
	s_add_i32 m0, s34, 0x2000
	s_nop 0
	global_load_lds_dwordx4 v[222:223], off
	v_lshl_add_u64 v[222:223], v[226:227], 0, s[14:15]
	s_mov_b32 m0, s41
	s_nop 0
	global_load_lds_dwordx4 v[222:223], off
	v_lshl_add_u64 v[222:223], v[228:229], 0, s[14:15]
	s_mov_b32 m0, s42
	s_nop 0
	global_load_lds_dwordx4 v[222:223], off
	s_waitcnt vmcnt(8)
	s_waitcnt lgkmcnt(0)
	s_barrier
	s_setprio 0
	s_waitcnt lgkmcnt(0)
	v_mfma_f32_16x16x32_bf16 v[62:65], v[148:151], v[188:191], v[62:65]
	v_mfma_f32_16x16x32_bf16 v[58:61], v[156:159], v[188:191], v[58:61]
	v_mfma_f32_16x16x32_bf16 v[54:57], v[148:151], v[196:199], v[54:57]
	v_mfma_f32_16x16x32_bf16 v[46:49], v[156:159], v[196:199], v[46:49]
	v_mfma_f32_16x16x32_bf16 v[38:41], v[148:151], v[206:209], v[38:41]
	v_mfma_f32_16x16x32_bf16 v[30:33], v[156:159], v[206:209], v[30:33]
	v_mfma_f32_16x16x32_bf16 v[22:25], v[148:151], v[214:217], v[22:25]
	v_mfma_f32_16x16x32_bf16 v[14:17], v[156:159], v[214:217], v[14:17]
	v_mfma_f32_16x16x32_bf16 v[62:65], v[152:155], v[192:195], v[62:65]
	v_mfma_f32_16x16x32_bf16 v[58:61], v[160:163], v[192:195], v[58:61]
	v_mfma_f32_16x16x32_bf16 v[54:57], v[152:155], v[202:205], v[54:57]
	v_mfma_f32_16x16x32_bf16 v[46:49], v[160:163], v[202:205], v[46:49]
	v_mfma_f32_16x16x32_bf16 v[38:41], v[152:155], v[210:213], v[38:41]
	v_mfma_f32_16x16x32_bf16 v[30:33], v[160:163], v[210:213], v[30:33]
	v_mfma_f32_16x16x32_bf16 v[22:25], v[152:155], v[218:221], v[22:25]
	v_mfma_f32_16x16x32_bf16 v[14:17], v[160:163], v[218:221], v[14:17]
	v_mfma_f32_16x16x32_bf16 v[50:53], v[172:175], v[188:191], v[50:53]
	v_mfma_f32_16x16x32_bf16 v[42:45], v[180:183], v[188:191], v[42:45]
	v_mfma_f32_16x16x32_bf16 v[34:37], v[172:175], v[196:199], v[34:37]
	v_mfma_f32_16x16x32_bf16 v[26:29], v[180:183], v[196:199], v[26:29]
	v_mfma_f32_16x16x32_bf16 v[18:21], v[172:175], v[206:209], v[18:21]
	v_mfma_f32_16x16x32_bf16 v[10:13], v[180:183], v[206:209], v[10:13]
	v_mfma_f32_16x16x32_bf16 v[6:9], v[172:175], v[214:217], v[6:9]
	v_mfma_f32_16x16x32_bf16 v[2:5], v[180:183], v[214:217], v[2:5]
	v_mfma_f32_16x16x32_bf16 v[50:53], v[176:179], v[192:195], v[50:53]
	v_mfma_f32_16x16x32_bf16 v[42:45], v[184:187], v[192:195], v[42:45]
	v_mfma_f32_16x16x32_bf16 v[34:37], v[176:179], v[202:205], v[34:37]
	v_mfma_f32_16x16x32_bf16 v[26:29], v[184:187], v[202:205], v[26:29]
	v_mfma_f32_16x16x32_bf16 v[18:21], v[176:179], v[210:213], v[18:21]
	v_mfma_f32_16x16x32_bf16 v[10:13], v[184:187], v[210:213], v[10:13]
	v_mfma_f32_16x16x32_bf16 v[6:9], v[176:179], v[218:221], v[6:9]
	v_mfma_f32_16x16x32_bf16 v[2:5], v[184:187], v[218:221], v[2:5]
	s_setprio 1
	s_barrier
	s_add_i32 s48, s48, 2
	s_add_u32 s12, s12, 0x100
	s_addc_u32 s13, s13, 0
	s_add_u32 s25, s25, 0x100
	s_addc_u32 s47, s47, 0
	s_cmp_gt_u32 s48, 13
	s_cbranch_scc0 .LBB0_1134
	s_and_b64 vcc, exec, s[16:17]
	s_cbranch_vccz .LBB0_1137
	s_barrier

.LBB0_1299:
	ds_read_b128 v[106:109], v246
	ds_read_b128 v[118:121], v246 offset:1024
	ds_read_b128 v[122:125], v246 offset:2048
	ds_read_b128 v[134:137], v246 offset:3072
	ds_read_b128 v[138:141], v247
	ds_read_b128 v[142:145], v247 offset:1024
	ds_read_b128 v[146:149], v247 offset:2048
	ds_read_b128 v[158:161], v247 offset:3072
	s_add_u32 s30, s28, 0xfffe0080
	s_addc_u32 s31, s29, -1
	s_cmp_eq_u32 s49, 4
	s_cselect_b32 s35, s10, s31
	s_cselect_b32 s34, s11, s30
	s_cselect_b32 s31, s19, s48
	s_cselect_b32 s30, s21, s27
	v_lshl_add_u64 v[202:203], s[28:29], 0, v[198:199]
	s_add_i32 m0, s37, 0xc000
	ds_read_b128 v[162:165], v248
	ds_read_b128 v[166:169], v248 offset:1024
	ds_read_b128 v[170:173], v248 offset:2048
	ds_read_b128 v[174:177], v248 offset:3072
	ds_read_b128 v[178:181], v248 offset:4096
	ds_read_b128 v[182:185], v248 offset:5120
	ds_read_b128 v[186:189], v248 offset:6144
	ds_read_b128 v[206:209], v248 offset:7168
	global_load_lds_dwordx4 v[202:203], off
	v_lshl_add_u64 v[202:203], s[28:29], 0, v[200:201]
	s_add_i32 m0, s37, 0xe000
	s_nop 0
	global_load_lds_dwordx4 v[202:203], off
	s_waitcnt vmcnt(8)
	s_waitcnt lgkmcnt(0)
	s_barrier
	s_setprio 0
	s_waitcnt lgkmcnt(0)
	v_mfma_f32_16x16x32_bf16 v[154:157], v[106:109], v[162:165], v[154:157]
	v_mfma_f32_16x16x32_bf16 v[150:153], v[122:125], v[162:165], v[150:153]
	v_mfma_f32_16x16x32_bf16 v[114:117], v[106:109], v[170:173], v[114:117]
	v_mfma_f32_16x16x32_bf16 v[110:113], v[122:125], v[170:173], v[110:113]
	v_mfma_f32_16x16x32_bf16 v[94:97], v[106:109], v[178:181], v[94:97]
	v_mfma_f32_16x16x32_bf16 v[90:93], v[122:125], v[178:181], v[90:93]
	v_mfma_f32_16x16x32_bf16 v[78:81], v[106:109], v[186:189], v[78:81]
	v_mfma_f32_16x16x32_bf16 v[74:77], v[122:125], v[186:189], v[74:77]
	v_mfma_f32_16x16x32_bf16 v[154:157], v[118:121], v[166:169], v[154:157]
	v_mfma_f32_16x16x32_bf16 v[150:153], v[134:137], v[166:169], v[150:153]
	v_mfma_f32_16x16x32_bf16 v[114:117], v[118:121], v[174:177], v[114:117]
	v_mfma_f32_16x16x32_bf16 v[110:113], v[134:137], v[174:177], v[110:113]
	v_mfma_f32_16x16x32_bf16 v[94:97], v[118:121], v[182:185], v[94:97]
	v_mfma_f32_16x16x32_bf16 v[90:93], v[134:137], v[182:185], v[90:93]
	v_mfma_f32_16x16x32_bf16 v[78:81], v[118:121], v[206:209], v[78:81]
	v_mfma_f32_16x16x32_bf16 v[74:77], v[134:137], v[206:209], v[74:77]
	v_mfma_f32_16x16x32_bf16 v[130:133], v[138:141], v[162:165], v[130:133]
	v_mfma_f32_16x16x32_bf16 v[126:129], v[146:149], v[162:165], v[126:129]
	v_mfma_f32_16x16x32_bf16 v[102:105], v[138:141], v[170:173], v[102:105]
	v_mfma_f32_16x16x32_bf16 v[98:101], v[146:149], v[170:173], v[98:101]
	v_mfma_f32_16x16x32_bf16 v[86:89], v[138:141], v[178:181], v[86:89]
	v_mfma_f32_16x16x32_bf16 v[82:85], v[146:149], v[178:181], v[82:85]
	v_mfma_f32_16x16x32_bf16 v[70:73], v[138:141], v[186:189], v[70:73]
	v_mfma_f32_16x16x32_bf16 v[66:69], v[146:149], v[186:189], v[66:69]
	v_mfma_f32_16x16x32_bf16 v[130:133], v[142:145], v[166:169], v[130:133]
	v_mfma_f32_16x16x32_bf16 v[126:129], v[158:161], v[166:169], v[126:129]
	v_mfma_f32_16x16x32_bf16 v[102:105], v[142:145], v[174:177], v[102:105]
	v_mfma_f32_16x16x32_bf16 v[98:101], v[158:161], v[174:177], v[98:101]
	v_mfma_f32_16x16x32_bf16 v[86:89], v[142:145], v[182:185], v[86:89]
	v_mfma_f32_16x16x32_bf16 v[82:85], v[158:161], v[182:185], v[82:85]
	v_mfma_f32_16x16x32_bf16 v[70:73], v[142:145], v[206:209], v[70:73]
	v_mfma_f32_16x16x32_bf16 v[66:69], v[158:161], v[206:209], v[66:69]
	s_setprio 1
	s_barrier
	s_add_i32 s50, s80, s36
	v_lshl_add_u64 v[202:203], s[30:31], 0, v[192:193]
	s_mov_b32 m0, s50
	ds_read_b128 v[162:165], v248 offset:16384
	ds_read_b128 v[166:169], v248 offset:17408
	ds_read_b128 v[170:173], v248 offset:18432
	ds_read_b128 v[174:177], v248 offset:19456
	ds_read_b128 v[178:181], v248 offset:20480
	ds_read_b128 v[182:185], v248 offset:21504
	ds_read_b128 v[186:189], v248 offset:22528
	ds_read_b128 v[206:209], v248 offset:23552
	global_load_lds_dwordx4 v[202:203], off
	s_add_i32 m0, s50, 0x2000
	s_add_u32 s50, s30, 0x20000
	v_lshl_add_u64 v[204:205], s[30:31], 0, v[196:197]
	s_addc_u32 s51, s31, 0
	s_add_i32 s52, s46, s36
	global_load_lds_dwordx4 v[204:205], off
	v_lshl_add_u64 v[210:211], s[50:51], 0, v[192:193]
	s_mov_b32 m0, s52
	v_lshl_add_u64 v[212:213], s[34:35], 0, v[194:195]
	global_load_lds_dwordx4 v[210:211], off
	v_lshl_add_u64 v[210:211], s[50:51], 0, v[196:197]
	s_add_i32 m0, s52, 0x2000
	s_nop 0
	global_load_lds_dwordx4 v[210:211], off
	v_lshl_add_u64 v[210:211], s[34:35], 0, v[190:191]
	s_mov_b32 m0, s37
	s_nop 0
	global_load_lds_dwordx4 v[210:211], off
	s_mov_b32 m0, s38
	s_nop 0
	global_load_lds_dwordx4 v[212:213], off
	s_waitcnt vmcnt(8)
	s_waitcnt lgkmcnt(0)
	s_barrier
	s_setprio 0
	s_waitcnt lgkmcnt(0)
	v_mfma_f32_16x16x32_bf16 v[62:65], v[106:109], v[162:165], v[62:65]
	v_mfma_f32_16x16x32_bf16 v[58:61], v[122:125], v[162:165], v[58:61]
	v_mfma_f32_16x16x32_bf16 v[46:49], v[106:109], v[170:173], v[46:49]
	v_mfma_f32_16x16x32_bf16 v[42:45], v[122:125], v[170:173], v[42:45]
	v_mfma_f32_16x16x32_bf16 v[30:33], v[106:109], v[178:181], v[30:33]
	v_mfma_f32_16x16x32_bf16 v[26:29], v[122:125], v[178:181], v[26:29]
	v_mfma_f32_16x16x32_bf16 v[14:17], v[106:109], v[186:189], v[14:17]
	v_mfma_f32_16x16x32_bf16 v[10:13], v[122:125], v[186:189], v[10:13]
	v_mfma_f32_16x16x32_bf16 v[62:65], v[118:121], v[166:169], v[62:65]
	v_mfma_f32_16x16x32_bf16 v[58:61], v[134:137], v[166:169], v[58:61]
	v_mfma_f32_16x16x32_bf16 v[46:49], v[118:121], v[174:177], v[46:49]
	v_mfma_f32_16x16x32_bf16 v[42:45], v[134:137], v[174:177], v[42:45]
	v_mfma_f32_16x16x32_bf16 v[30:33], v[118:121], v[182:185], v[30:33]
	v_mfma_f32_16x16x32_bf16 v[26:29], v[134:137], v[182:185], v[26:29]
	v_mfma_f32_16x16x32_bf16 v[14:17], v[118:121], v[206:209], v[14:17]
	v_mfma_f32_16x16x32_bf16 v[10:13], v[134:137], v[206:209], v[10:13]
	v_mfma_f32_16x16x32_bf16 v[54:57], v[138:141], v[162:165], v[54:57]
	v_mfma_f32_16x16x32_bf16 v[50:53], v[146:149], v[162:165], v[50:53]
	v_mfma_f32_16x16x32_bf16 v[38:41], v[138:141], v[170:173], v[38:41]
	v_mfma_f32_16x16x32_bf16 v[34:37], v[146:149], v[170:173], v[34:37]
	v_mfma_f32_16x16x32_bf16 v[22:25], v[138:141], v[178:181], v[22:25]
	v_mfma_f32_16x16x32_bf16 v[18:21], v[146:149], v[178:181], v[18:21]
	v_mfma_f32_16x16x32_bf16 v[6:9], v[138:141], v[186:189], v[6:9]
	v_mfma_f32_16x16x32_bf16 v[2:5], v[146:149], v[186:189], v[2:5]
	v_mfma_f32_16x16x32_bf16 v[54:57], v[142:145], v[166:169], v[54:57]
	v_mfma_f32_16x16x32_bf16 v[50:53], v[158:161], v[166:169], v[50:53]
	v_mfma_f32_16x16x32_bf16 v[38:41], v[142:145], v[174:177], v[38:41]
	v_mfma_f32_16x16x32_bf16 v[34:37], v[158:161], v[174:177], v[34:37]
	v_mfma_f32_16x16x32_bf16 v[22:25], v[142:145], v[182:185], v[22:25]
	v_mfma_f32_16x16x32_bf16 v[18:21], v[158:161], v[182:185], v[18:21]
	v_mfma_f32_16x16x32_bf16 v[6:9], v[142:145], v[206:209], v[6:9]
	v_mfma_f32_16x16x32_bf16 v[2:5], v[158:161], v[206:209], v[2:5]
	s_setprio 1
	s_barrier
	s_add_i32 s50, 0, 0x18000
	s_add_i32 s51, 0, 0x1c000
	v_add_u32_e32 v134, s50, v244
	v_add_u32_e32 v158, s51, v244
	ds_read_b128 v[106:109], v134
	ds_read_b128 v[118:121], v134 offset:1024
	ds_read_b128 v[122:125], v134 offset:2048
	ds_read_b128 v[134:137], v134 offset:3072
	ds_read_b128 v[138:141], v158
	ds_read_b128 v[142:145], v158 offset:1024
	ds_read_b128 v[146:149], v158 offset:2048
	ds_read_b128 v[158:161], v158 offset:3072
	s_add_u32 s34, s34, 0x20000
	s_addc_u32 s35, s35, 0
	s_mov_b32 m0, s39
	v_lshl_add_u64 v[214:215], s[34:35], 0, v[190:191]
	ds_read_b128 v[162:165], v248 offset:32768
	ds_read_b128 v[166:169], v248 offset:33792
	ds_read_b128 v[170:173], v248 offset:34816
	ds_read_b128 v[174:177], v248 offset:35840
	ds_read_b128 v[178:181], v248 offset:36864
	ds_read_b128 v[182:185], v248 offset:37888
	ds_read_b128 v[186:189], v248 offset:38912
	ds_read_b128 v[206:209], v248 offset:39936
	global_load_lds_dwordx4 v[214:215], off
	v_lshl_add_u64 v[214:215], s[34:35], 0, v[194:195]
	s_mov_b32 m0, s40
	s_nop 0
	global_load_lds_dwordx4 v[214:215], off
	s_waitcnt vmcnt(8)
	s_waitcnt lgkmcnt(0)
	s_barrier
	s_setprio 0
	s_waitcnt lgkmcnt(0)
	v_mfma_f32_16x16x32_bf16 v[154:157], v[106:109], v[162:165], v[154:157]
	v_mfma_f32_16x16x32_bf16 v[150:153], v[122:125], v[162:165], v[150:153]
	v_mfma_f32_16x16x32_bf16 v[114:117], v[106:109], v[170:173], v[114:117]
	v_mfma_f32_16x16x32_bf16 v[110:113], v[122:125], v[170:173], v[110:113]
	v_mfma_f32_16x16x32_bf16 v[94:97], v[106:109], v[178:181], v[94:97]
	v_mfma_f32_16x16x32_bf16 v[90:93], v[122:125], v[178:181], v[90:93]
	v_mfma_f32_16x16x32_bf16 v[78:81], v[106:109], v[186:189], v[78:81]
	v_mfma_f32_16x16x32_bf16 v[74:77], v[122:125], v[186:189], v[74:77]
	v_mfma_f32_16x16x32_bf16 v[154:157], v[118:121], v[166:169], v[154:157]
	v_mfma_f32_16x16x32_bf16 v[150:153], v[134:137], v[166:169], v[150:153]
	v_mfma_f32_16x16x32_bf16 v[114:117], v[118:121], v[174:177], v[114:117]
	v_mfma_f32_16x16x32_bf16 v[110:113], v[134:137], v[174:177], v[110:113]
	v_mfma_f32_16x16x32_bf16 v[94:97], v[118:121], v[182:185], v[94:97]
	v_mfma_f32_16x16x32_bf16 v[90:93], v[134:137], v[182:185], v[90:93]
	v_mfma_f32_16x16x32_bf16 v[78:81], v[118:121], v[206:209], v[78:81]
	v_mfma_f32_16x16x32_bf16 v[74:77], v[134:137], v[206:209], v[74:77]
	v_mfma_f32_16x16x32_bf16 v[130:133], v[138:141], v[162:165], v[130:133]
	v_mfma_f32_16x16x32_bf16 v[126:129], v[146:149], v[162:165], v[126:129]
	v_mfma_f32_16x16x32_bf16 v[102:105], v[138:141], v[170:173], v[102:105]
	v_mfma_f32_16x16x32_bf16 v[98:101], v[146:149], v[170:173], v[98:101]
	v_mfma_f32_16x16x32_bf16 v[86:89], v[138:141], v[178:181], v[86:89]
	v_mfma_f32_16x16x32_bf16 v[82:85], v[146:149], v[178:181], v[82:85]
	v_mfma_f32_16x16x32_bf16 v[70:73], v[138:141], v[186:189], v[70:73]
	v_mfma_f32_16x16x32_bf16 v[66:69], v[146:149], v[186:189], v[66:69]
	v_mfma_f32_16x16x32_bf16 v[130:133], v[142:145], v[166:169], v[130:133]
	v_mfma_f32_16x16x32_bf16 v[126:129], v[158:161], v[166:169], v[126:129]
	v_mfma_f32_16x16x32_bf16 v[102:105], v[142:145], v[174:177], v[102:105]
	v_mfma_f32_16x16x32_bf16 v[98:101], v[158:161], v[174:177], v[98:101]
	v_mfma_f32_16x16x32_bf16 v[86:89], v[142:145], v[182:185], v[86:89]
	v_mfma_f32_16x16x32_bf16 v[82:85], v[158:161], v[182:185], v[82:85]
	v_mfma_f32_16x16x32_bf16 v[70:73], v[142:145], v[206:209], v[70:73]
	v_mfma_f32_16x16x32_bf16 v[66:69], v[158:161], v[206:209], v[66:69]
	s_setprio 1
	s_barrier
	s_add_i32 s34, s50, s36
	v_lshl_add_u64 v[202:203], v[202:203], 0, s[14:15]
	s_mov_b32 m0, s34
	ds_read_b128 v[162:165], v248 offset:49152
	ds_read_b128 v[166:169], v248 offset:50176
	ds_read_b128 v[170:173], v248 offset:51200
	ds_read_b128 v[174:177], v248 offset:52224
	ds_read_b128 v[178:181], v248 offset:53248
	ds_read_b128 v[182:185], v248 offset:54272
	ds_read_b128 v[186:189], v248 offset:55296
	ds_read_b128 v[206:209], v248 offset:56320
	global_load_lds_dwordx4 v[202:203], off
	s_add_i32 m0, s34, 0x2000
	s_add_u32 s30, s30, 0x20080
	v_lshl_add_u64 v[202:203], v[204:205], 0, s[14:15]
	s_addc_u32 s31, s31, 0
	s_add_i32 s34, s51, s36
	global_load_lds_dwordx4 v[202:203], off
	v_lshl_add_u64 v[202:203], s[30:31], 0, v[192:193]
	s_mov_b32 m0, s34
	s_nop 0
	global_load_lds_dwordx4 v[202:203], off
	v_lshl_add_u64 v[202:203], s[30:31], 0, v[196:197]
	s_add_i32 m0, s34, 0x2000
	s_nop 0
	global_load_lds_dwordx4 v[202:203], off
	v_lshl_add_u64 v[202:203], v[210:211], 0, s[14:15]
	s_mov_b32 m0, s42
	s_nop 0
	global_load_lds_dwordx4 v[202:203], off
	v_lshl_add_u64 v[202:203], v[212:213], 0, s[14:15]
	s_mov_b32 m0, s43
	s_nop 0
	global_load_lds_dwordx4 v[202:203], off
	s_waitcnt vmcnt(8)
	s_waitcnt lgkmcnt(0)
	s_barrier
	s_setprio 0
	s_waitcnt lgkmcnt(0)
	v_mfma_f32_16x16x32_bf16 v[62:65], v[106:109], v[162:165], v[62:65]
	v_mfma_f32_16x16x32_bf16 v[58:61], v[122:125], v[162:165], v[58:61]
	v_mfma_f32_16x16x32_bf16 v[46:49], v[106:109], v[170:173], v[46:49]
	v_mfma_f32_16x16x32_bf16 v[42:45], v[122:125], v[170:173], v[42:45]
	v_mfma_f32_16x16x32_bf16 v[30:33], v[106:109], v[178:181], v[30:33]
	v_mfma_f32_16x16x32_bf16 v[26:29], v[122:125], v[178:181], v[26:29]
	v_mfma_f32_16x16x32_bf16 v[14:17], v[106:109], v[186:189], v[14:17]
	v_mfma_f32_16x16x32_bf16 v[10:13], v[122:125], v[186:189], v[10:13]
	v_mfma_f32_16x16x32_bf16 v[62:65], v[118:121], v[166:169], v[62:65]
	v_mfma_f32_16x16x32_bf16 v[58:61], v[134:137], v[166:169], v[58:61]
	v_mfma_f32_16x16x32_bf16 v[46:49], v[118:121], v[174:177], v[46:49]
	v_mfma_f32_16x16x32_bf16 v[42:45], v[134:137], v[174:177], v[42:45]
	v_mfma_f32_16x16x32_bf16 v[30:33], v[118:121], v[182:185], v[30:33]
	v_mfma_f32_16x16x32_bf16 v[26:29], v[134:137], v[182:185], v[26:29]
	v_mfma_f32_16x16x32_bf16 v[14:17], v[118:121], v[206:209], v[14:17]
	v_mfma_f32_16x16x32_bf16 v[10:13], v[134:137], v[206:209], v[10:13]
	v_mfma_f32_16x16x32_bf16 v[54:57], v[138:141], v[162:165], v[54:57]
	v_mfma_f32_16x16x32_bf16 v[50:53], v[146:149], v[162:165], v[50:53]
	v_mfma_f32_16x16x32_bf16 v[38:41], v[138:141], v[170:173], v[38:41]
	v_mfma_f32_16x16x32_bf16 v[34:37], v[146:149], v[170:173], v[34:37]
	v_mfma_f32_16x16x32_bf16 v[22:25], v[138:141], v[178:181], v[22:25]
	v_mfma_f32_16x16x32_bf16 v[18:21], v[146:149], v[178:181], v[18:21]
	v_mfma_f32_16x16x32_bf16 v[6:9], v[138:141], v[186:189], v[6:9]
	v_mfma_f32_16x16x32_bf16 v[2:5], v[146:149], v[186:189], v[2:5]
	v_mfma_f32_16x16x32_bf16 v[54:57], v[142:145], v[166:169], v[54:57]
	v_mfma_f32_16x16x32_bf16 v[50:53], v[158:161], v[166:169], v[50:53]
	v_mfma_f32_16x16x32_bf16 v[38:41], v[142:145], v[174:177], v[38:41]
	v_mfma_f32_16x16x32_bf16 v[34:37], v[158:161], v[174:177], v[34:37]
	v_mfma_f32_16x16x32_bf16 v[22:25], v[142:145], v[182:185], v[22:25]
	v_mfma_f32_16x16x32_bf16 v[18:21], v[158:161], v[182:185], v[18:21]
	v_mfma_f32_16x16x32_bf16 v[6:9], v[142:145], v[206:209], v[6:9]
	v_mfma_f32_16x16x32_bf16 v[2:5], v[158:161], v[206:209], v[2:5]
	s_setprio 1
	s_barrier
	s_add_i32 s49, s49, 2
	s_add_u32 s28, s28, 0x100
	s_addc_u32 s29, s29, 0
	s_add_u32 s27, s27, 0x100
	s_addc_u32 s48, s48, 0
	s_cmp_gt_u32 s49, 5
	s_cbranch_scc0 .LBB0_1299
	s_and_b64 vcc, exec, s[16:17]
	s_cbranch_vccz .LBB0_1302
	s_barrier

.LBB0_1400:
	ds_read_b128 v[148:151], v169
	ds_read_b128 v[156:159], v169 offset:1024
	ds_read_b128 v[176:179], v169 offset:2048
	ds_read_b128 v[180:183], v169 offset:3072
	ds_read_b128 v[184:187], v173
	ds_read_b128 v[188:191], v173 offset:1024
	ds_read_b128 v[192:195], v173 offset:2048
	ds_read_b128 v[196:199], v173 offset:3072
	s_add_u32 s30, s4, 0xfffc0080
	s_addc_u32 s31, s5, -1
	s_cmp_eq_u32 s48, 12
	s_cselect_b32 s35, s3, s31
	s_cselect_b32 s34, s10, s30
	s_cselect_b32 s31, s11, s47
	s_cselect_b32 s30, s23, s25
	v_lshl_add_u64 v[152:153], s[4:5], 0, v[140:141]
	s_add_i32 m0, s36, 0xc000
	ds_read_b128 v[200:203], v175
	ds_read_b128 v[204:207], v175 offset:1024
	ds_read_b128 v[208:211], v175 offset:2048
	ds_read_b128 v[212:215], v175 offset:3072
	ds_read_b128 v[216:219], v175 offset:4096
	ds_read_b128 v[220:223], v175 offset:5120
	ds_read_b128 v[224:227], v175 offset:6144
	ds_read_b128 v[228:231], v175 offset:7168
	global_load_lds_dwordx4 v[152:153], off
	v_lshl_add_u64 v[152:153], s[4:5], 0, v[142:143]
	s_add_i32 m0, s36, 0xe000
	s_nop 0
	global_load_lds_dwordx4 v[152:153], off
	s_waitcnt vmcnt(8)
	s_waitcnt lgkmcnt(0)
	s_barrier
	s_setprio 0
	s_waitcnt lgkmcnt(0)
	v_mfma_f32_16x16x32_bf16 v[126:129], v[148:151], v[200:203], v[126:129]
	v_mfma_f32_16x16x32_bf16 v[122:125], v[176:179], v[200:203], v[122:125]
	v_mfma_f32_16x16x32_bf16 v[110:113], v[148:151], v[208:211], v[110:113]
	v_mfma_f32_16x16x32_bf16 v[106:109], v[176:179], v[208:211], v[106:109]
	v_mfma_f32_16x16x32_bf16 v[94:97], v[148:151], v[216:219], v[94:97]
	v_mfma_f32_16x16x32_bf16 v[90:93], v[176:179], v[216:219], v[90:93]
	v_mfma_f32_16x16x32_bf16 v[78:81], v[148:151], v[224:227], v[78:81]
	v_mfma_f32_16x16x32_bf16 v[74:77], v[176:179], v[224:227], v[74:77]
	v_mfma_f32_16x16x32_bf16 v[126:129], v[156:159], v[204:207], v[126:129]
	v_mfma_f32_16x16x32_bf16 v[122:125], v[180:183], v[204:207], v[122:125]
	v_mfma_f32_16x16x32_bf16 v[110:113], v[156:159], v[212:215], v[110:113]
	v_mfma_f32_16x16x32_bf16 v[106:109], v[180:183], v[212:215], v[106:109]
	v_mfma_f32_16x16x32_bf16 v[94:97], v[156:159], v[220:223], v[94:97]
	v_mfma_f32_16x16x32_bf16 v[90:93], v[180:183], v[220:223], v[90:93]
	v_mfma_f32_16x16x32_bf16 v[78:81], v[156:159], v[228:231], v[78:81]
	v_mfma_f32_16x16x32_bf16 v[74:77], v[180:183], v[228:231], v[74:77]
	v_mfma_f32_16x16x32_bf16 v[118:121], v[184:187], v[200:203], v[118:121]
	v_mfma_f32_16x16x32_bf16 v[114:117], v[192:195], v[200:203], v[114:117]
	v_mfma_f32_16x16x32_bf16 v[102:105], v[184:187], v[208:211], v[102:105]
	v_mfma_f32_16x16x32_bf16 v[98:101], v[192:195], v[208:211], v[98:101]
	v_mfma_f32_16x16x32_bf16 v[86:89], v[184:187], v[216:219], v[86:89]
	v_mfma_f32_16x16x32_bf16 v[82:85], v[192:195], v[216:219], v[82:85]
	v_mfma_f32_16x16x32_bf16 v[70:73], v[184:187], v[224:227], v[70:73]
	v_mfma_f32_16x16x32_bf16 v[66:69], v[192:195], v[224:227], v[66:69]
	v_mfma_f32_16x16x32_bf16 v[118:121], v[188:191], v[204:207], v[118:121]
	v_mfma_f32_16x16x32_bf16 v[114:117], v[196:199], v[204:207], v[114:117]
	v_mfma_f32_16x16x32_bf16 v[102:105], v[188:191], v[212:215], v[102:105]
	v_mfma_f32_16x16x32_bf16 v[98:101], v[196:199], v[212:215], v[98:101]
	v_mfma_f32_16x16x32_bf16 v[86:89], v[188:191], v[220:223], v[86:89]
	v_mfma_f32_16x16x32_bf16 v[82:85], v[196:199], v[220:223], v[82:85]
	v_mfma_f32_16x16x32_bf16 v[70:73], v[188:191], v[228:231], v[70:73]
	v_mfma_f32_16x16x32_bf16 v[66:69], v[196:199], v[228:231], v[66:69]
	s_setprio 1
	s_barrier
	s_add_i32 s49, s80, s21
	v_lshl_add_u64 v[152:153], s[30:31], 0, v[132:133]
	s_mov_b32 m0, s49
	ds_read_b128 v[200:203], v175 offset:16384
	ds_read_b128 v[204:207], v175 offset:17408
	ds_read_b128 v[208:211], v175 offset:18432
	ds_read_b128 v[212:215], v175 offset:19456
	ds_read_b128 v[216:219], v175 offset:20480
	ds_read_b128 v[220:223], v175 offset:21504
	ds_read_b128 v[224:227], v175 offset:22528
	ds_read_b128 v[228:231], v175 offset:23552
	global_load_lds_dwordx4 v[152:153], off
	s_add_i32 m0, s49, 0x2000
	s_add_u32 s50, s30, 0x40000
	v_lshl_add_u64 v[160:161], s[30:31], 0, v[136:137]
	s_addc_u32 s51, s31, 0
	s_add_i32 s49, s44, s21
	global_load_lds_dwordx4 v[160:161], off
	v_lshl_add_u64 v[164:165], s[50:51], 0, v[132:133]
	s_mov_b32 m0, s49
	v_lshl_add_u64 v[170:171], s[34:35], 0, v[134:135]
	global_load_lds_dwordx4 v[164:165], off
	v_lshl_add_u64 v[164:165], s[50:51], 0, v[136:137]
	s_add_i32 m0, s49, 0x2000
	s_nop 0
	global_load_lds_dwordx4 v[164:165], off
	v_lshl_add_u64 v[164:165], s[34:35], 0, v[130:131]
	s_mov_b32 m0, s36
	s_nop 0
	global_load_lds_dwordx4 v[164:165], off
	s_mov_b32 m0, s37
	s_nop 0
	global_load_lds_dwordx4 v[170:171], off
	s_waitcnt vmcnt(8)
	s_waitcnt lgkmcnt(0)
	s_barrier
	s_setprio 0
	s_waitcnt lgkmcnt(0)
	v_mfma_f32_16x16x32_bf16 v[62:65], v[148:151], v[200:203], v[62:65]
	v_mfma_f32_16x16x32_bf16 v[58:61], v[176:179], v[200:203], v[58:61]
	v_mfma_f32_16x16x32_bf16 v[46:49], v[148:151], v[208:211], v[46:49]
	v_mfma_f32_16x16x32_bf16 v[42:45], v[176:179], v[208:211], v[42:45]
	v_mfma_f32_16x16x32_bf16 v[30:33], v[148:151], v[216:219], v[30:33]
	v_mfma_f32_16x16x32_bf16 v[26:29], v[176:179], v[216:219], v[26:29]
	v_mfma_f32_16x16x32_bf16 v[14:17], v[148:151], v[224:227], v[14:17]
	v_mfma_f32_16x16x32_bf16 v[10:13], v[176:179], v[224:227], v[10:13]
	v_mfma_f32_16x16x32_bf16 v[62:65], v[156:159], v[204:207], v[62:65]
	v_mfma_f32_16x16x32_bf16 v[58:61], v[180:183], v[204:207], v[58:61]
	v_mfma_f32_16x16x32_bf16 v[46:49], v[156:159], v[212:215], v[46:49]
	v_mfma_f32_16x16x32_bf16 v[42:45], v[180:183], v[212:215], v[42:45]
	v_mfma_f32_16x16x32_bf16 v[30:33], v[156:159], v[220:223], v[30:33]
	v_mfma_f32_16x16x32_bf16 v[26:29], v[180:183], v[220:223], v[26:29]
	v_mfma_f32_16x16x32_bf16 v[14:17], v[156:159], v[228:231], v[14:17]
	v_mfma_f32_16x16x32_bf16 v[10:13], v[180:183], v[228:231], v[10:13]
	v_mfma_f32_16x16x32_bf16 v[54:57], v[184:187], v[200:203], v[54:57]
	v_mfma_f32_16x16x32_bf16 v[50:53], v[192:195], v[200:203], v[50:53]
	v_mfma_f32_16x16x32_bf16 v[38:41], v[184:187], v[208:211], v[38:41]
	v_mfma_f32_16x16x32_bf16 v[34:37], v[192:195], v[208:211], v[34:37]
	v_mfma_f32_16x16x32_bf16 v[22:25], v[184:187], v[216:219], v[22:25]
	v_mfma_f32_16x16x32_bf16 v[18:21], v[192:195], v[216:219], v[18:21]
	v_mfma_f32_16x16x32_bf16 v[6:9], v[184:187], v[224:227], v[6:9]
	v_mfma_f32_16x16x32_bf16 v[2:5], v[192:195], v[224:227], v[2:5]
	v_mfma_f32_16x16x32_bf16 v[54:57], v[188:191], v[204:207], v[54:57]
	v_mfma_f32_16x16x32_bf16 v[50:53], v[196:199], v[204:207], v[50:53]
	v_mfma_f32_16x16x32_bf16 v[38:41], v[188:191], v[212:215], v[38:41]
	v_mfma_f32_16x16x32_bf16 v[34:37], v[196:199], v[212:215], v[34:37]
	v_mfma_f32_16x16x32_bf16 v[22:25], v[188:191], v[220:223], v[22:25]
	v_mfma_f32_16x16x32_bf16 v[18:21], v[196:199], v[220:223], v[18:21]
	v_mfma_f32_16x16x32_bf16 v[6:9], v[188:191], v[228:231], v[6:9]
	v_mfma_f32_16x16x32_bf16 v[2:5], v[196:199], v[228:231], v[2:5]
	s_setprio 1
	s_barrier
	s_add_i32 s49, 0, 0x18000
	v_add_u32_e32 v154, s49, v163
	s_add_i32 s50, 0, 0x1c000
	ds_read_b128 v[148:151], v154
	ds_read_b128 v[156:159], v154 offset:1024
	ds_read_b128 v[176:179], v154 offset:2048
	ds_read_b128 v[180:183], v154 offset:3072
	v_add_u32_e32 v154, s50, v163
	ds_read_b128 v[184:187], v154
	ds_read_b128 v[188:191], v154 offset:1024
	ds_read_b128 v[192:195], v154 offset:2048
	ds_read_b128 v[196:199], v154 offset:3072
	s_add_u32 s34, s34, 0x40000
	s_addc_u32 s35, s35, 0
	s_mov_b32 m0, s38
	v_lshl_add_u64 v[232:233], s[34:35], 0, v[130:131]
	ds_read_b128 v[200:203], v175 offset:32768
	ds_read_b128 v[204:207], v175 offset:33792
	ds_read_b128 v[208:211], v175 offset:34816
	ds_read_b128 v[212:215], v175 offset:35840
	ds_read_b128 v[216:219], v175 offset:36864
	ds_read_b128 v[220:223], v175 offset:37888
	ds_read_b128 v[224:227], v175 offset:38912
	ds_read_b128 v[228:231], v175 offset:39936
	global_load_lds_dwordx4 v[232:233], off
	v_lshl_add_u64 v[232:233], s[34:35], 0, v[134:135]
	s_mov_b32 m0, s39
	s_nop 0
	global_load_lds_dwordx4 v[232:233], off
	s_waitcnt vmcnt(8)
	s_waitcnt lgkmcnt(0)
	s_barrier
	s_setprio 0
	s_waitcnt lgkmcnt(0)
	v_mfma_f32_16x16x32_bf16 v[126:129], v[148:151], v[200:203], v[126:129]
	v_mfma_f32_16x16x32_bf16 v[122:125], v[176:179], v[200:203], v[122:125]
	v_mfma_f32_16x16x32_bf16 v[110:113], v[148:151], v[208:211], v[110:113]
	v_mfma_f32_16x16x32_bf16 v[106:109], v[176:179], v[208:211], v[106:109]
	v_mfma_f32_16x16x32_bf16 v[94:97], v[148:151], v[216:219], v[94:97]
	v_mfma_f32_16x16x32_bf16 v[90:93], v[176:179], v[216:219], v[90:93]
	v_mfma_f32_16x16x32_bf16 v[78:81], v[148:151], v[224:227], v[78:81]
	v_mfma_f32_16x16x32_bf16 v[74:77], v[176:179], v[224:227], v[74:77]
	v_mfma_f32_16x16x32_bf16 v[126:129], v[156:159], v[204:207], v[126:129]
	v_mfma_f32_16x16x32_bf16 v[122:125], v[180:183], v[204:207], v[122:125]
	v_mfma_f32_16x16x32_bf16 v[110:113], v[156:159], v[212:215], v[110:113]
	v_mfma_f32_16x16x32_bf16 v[106:109], v[180:183], v[212:215], v[106:109]
	v_mfma_f32_16x16x32_bf16 v[94:97], v[156:159], v[220:223], v[94:97]
	v_mfma_f32_16x16x32_bf16 v[90:93], v[180:183], v[220:223], v[90:93]
	v_mfma_f32_16x16x32_bf16 v[78:81], v[156:159], v[228:231], v[78:81]
	v_mfma_f32_16x16x32_bf16 v[74:77], v[180:183], v[228:231], v[74:77]
	v_mfma_f32_16x16x32_bf16 v[118:121], v[184:187], v[200:203], v[118:121]
	v_mfma_f32_16x16x32_bf16 v[114:117], v[192:195], v[200:203], v[114:117]
	v_mfma_f32_16x16x32_bf16 v[102:105], v[184:187], v[208:211], v[102:105]
	v_mfma_f32_16x16x32_bf16 v[98:101], v[192:195], v[208:211], v[98:101]
	v_mfma_f32_16x16x32_bf16 v[86:89], v[184:187], v[216:219], v[86:89]
	v_mfma_f32_16x16x32_bf16 v[82:85], v[192:195], v[216:219], v[82:85]
	v_mfma_f32_16x16x32_bf16 v[70:73], v[184:187], v[224:227], v[70:73]
	v_mfma_f32_16x16x32_bf16 v[66:69], v[192:195], v[224:227], v[66:69]
	v_mfma_f32_16x16x32_bf16 v[118:121], v[188:191], v[204:207], v[118:121]
	v_mfma_f32_16x16x32_bf16 v[114:117], v[196:199], v[204:207], v[114:117]
	v_mfma_f32_16x16x32_bf16 v[102:105], v[188:191], v[212:215], v[102:105]
	v_mfma_f32_16x16x32_bf16 v[98:101], v[196:199], v[212:215], v[98:101]
	v_mfma_f32_16x16x32_bf16 v[86:89], v[188:191], v[220:223], v[86:89]
	v_mfma_f32_16x16x32_bf16 v[82:85], v[196:199], v[220:223], v[82:85]
	v_mfma_f32_16x16x32_bf16 v[70:73], v[188:191], v[228:231], v[70:73]
	v_mfma_f32_16x16x32_bf16 v[66:69], v[196:199], v[228:231], v[66:69]
	s_setprio 1
	s_barrier
	s_add_i32 s34, s49, s21
	v_lshl_add_u64 v[152:153], v[152:153], 0, s[14:15]
	s_mov_b32 m0, s34
	ds_read_b128 v[200:203], v175 offset:49152
	ds_read_b128 v[204:207], v175 offset:50176
	ds_read_b128 v[208:211], v175 offset:51200
	ds_read_b128 v[212:215], v175 offset:52224
	ds_read_b128 v[216:219], v175 offset:53248
	ds_read_b128 v[220:223], v175 offset:54272
	ds_read_b128 v[224:227], v175 offset:55296
	ds_read_b128 v[228:231], v175 offset:56320
	global_load_lds_dwordx4 v[152:153], off
	s_add_i32 m0, s34, 0x2000
	s_add_u32 s30, s30, 0x40080
	v_lshl_add_u64 v[152:153], v[160:161], 0, s[14:15]
	s_addc_u32 s31, s31, 0
	s_add_i32 s34, s50, s21
	global_load_lds_dwordx4 v[152:153], off
	v_lshl_add_u64 v[152:153], s[30:31], 0, v[132:133]
	s_mov_b32 m0, s34
	s_nop 0
	global_load_lds_dwordx4 v[152:153], off
	v_lshl_add_u64 v[152:153], s[30:31], 0, v[136:137]
	s_add_i32 m0, s34, 0x2000
	s_nop 0
	global_load_lds_dwordx4 v[152:153], off
	v_lshl_add_u64 v[152:153], v[164:165], 0, s[14:15]
	s_mov_b32 m0, s41
	s_nop 0
	global_load_lds_dwordx4 v[152:153], off
	v_lshl_add_u64 v[152:153], v[170:171], 0, s[14:15]
	s_mov_b32 m0, s42
	s_nop 0
	global_load_lds_dwordx4 v[152:153], off
	s_waitcnt vmcnt(8)
	s_waitcnt lgkmcnt(0)
	s_barrier
	s_setprio 0
	s_waitcnt lgkmcnt(0)
	v_mfma_f32_16x16x32_bf16 v[62:65], v[148:151], v[200:203], v[62:65]
	v_mfma_f32_16x16x32_bf16 v[58:61], v[176:179], v[200:203], v[58:61]
	v_mfma_f32_16x16x32_bf16 v[46:49], v[148:151], v[208:211], v[46:49]
	v_mfma_f32_16x16x32_bf16 v[42:45], v[176:179], v[208:211], v[42:45]
	v_mfma_f32_16x16x32_bf16 v[30:33], v[148:151], v[216:219], v[30:33]
	v_mfma_f32_16x16x32_bf16 v[26:29], v[176:179], v[216:219], v[26:29]
	v_mfma_f32_16x16x32_bf16 v[14:17], v[148:151], v[224:227], v[14:17]
	v_mfma_f32_16x16x32_bf16 v[10:13], v[176:179], v[224:227], v[10:13]
	v_mfma_f32_16x16x32_bf16 v[62:65], v[156:159], v[204:207], v[62:65]
	v_mfma_f32_16x16x32_bf16 v[58:61], v[180:183], v[204:207], v[58:61]
	v_mfma_f32_16x16x32_bf16 v[46:49], v[156:159], v[212:215], v[46:49]
	v_mfma_f32_16x16x32_bf16 v[42:45], v[180:183], v[212:215], v[42:45]
	v_mfma_f32_16x16x32_bf16 v[30:33], v[156:159], v[220:223], v[30:33]
	v_mfma_f32_16x16x32_bf16 v[26:29], v[180:183], v[220:223], v[26:29]
	v_mfma_f32_16x16x32_bf16 v[14:17], v[156:159], v[228:231], v[14:17]
	v_mfma_f32_16x16x32_bf16 v[10:13], v[180:183], v[228:231], v[10:13]
	v_mfma_f32_16x16x32_bf16 v[54:57], v[184:187], v[200:203], v[54:57]
	v_mfma_f32_16x16x32_bf16 v[50:53], v[192:195], v[200:203], v[50:53]
	v_mfma_f32_16x16x32_bf16 v[38:41], v[184:187], v[208:211], v[38:41]
	v_mfma_f32_16x16x32_bf16 v[34:37], v[192:195], v[208:211], v[34:37]
	v_mfma_f32_16x16x32_bf16 v[22:25], v[184:187], v[216:219], v[22:25]
	v_mfma_f32_16x16x32_bf16 v[18:21], v[192:195], v[216:219], v[18:21]
	v_mfma_f32_16x16x32_bf16 v[6:9], v[184:187], v[224:227], v[6:9]
	v_mfma_f32_16x16x32_bf16 v[2:5], v[192:195], v[224:227], v[2:5]
	v_mfma_f32_16x16x32_bf16 v[54:57], v[188:191], v[204:207], v[54:57]
	v_mfma_f32_16x16x32_bf16 v[50:53], v[196:199], v[204:207], v[50:53]
	v_mfma_f32_16x16x32_bf16 v[38:41], v[188:191], v[212:215], v[38:41]
	v_mfma_f32_16x16x32_bf16 v[34:37], v[196:199], v[212:215], v[34:37]
	v_mfma_f32_16x16x32_bf16 v[22:25], v[188:191], v[220:223], v[22:25]
	v_mfma_f32_16x16x32_bf16 v[18:21], v[196:199], v[220:223], v[18:21]
	v_mfma_f32_16x16x32_bf16 v[6:9], v[188:191], v[228:231], v[6:9]
	v_mfma_f32_16x16x32_bf16 v[2:5], v[196:199], v[228:231], v[2:5]
	s_setprio 1
	s_barrier
	s_add_i32 s48, s48, 2
	s_add_u32 s4, s4, 0x100
	s_addc_u32 s5, s5, 0
	s_add_u32 s25, s25, 0x100
	s_addc_u32 s47, s47, 0
	s_cmp_gt_u32 s48, 13
	s_cbranch_scc0 .LBB0_1400
	s_and_b64 vcc, exec, s[16:17]
	s_cbranch_vccz .LBB0_1403
	s_barrier

.LBB0_1485:
	ds_read_b128 v[142:145], v194
	ds_read_b128 v[146:149], v194 offset:1024
	ds_read_b128 v[150:153], v194 offset:2048
	ds_read_b128 v[154:157], v194 offset:3072
	ds_read_b128 v[158:161], v195
	ds_read_b128 v[162:165], v195 offset:1024
	ds_read_b128 v[166:169], v195 offset:2048
	ds_read_b128 v[170:173], v195 offset:3072
	s_add_u32 s22, s20, 0xfff00080
	s_addc_u32 s23, s21, -1
	s_cmp_eq_u32 s43, 60
	s_cselect_b32 s25, s13, s23
	s_cselect_b32 s24, s39, s22
	s_cselect_b32 s23, s11, s42
	s_cselect_b32 s22, s40, s41
	v_lshl_add_u64 v[190:191], s[20:21], 0, v[134:135]
	s_add_i32 m0, s19, 0xc000
	ds_read_b128 v[174:177], v196
	ds_read_b128 v[178:181], v196 offset:1024
	ds_read_b128 v[182:185], v196 offset:2048
	ds_read_b128 v[186:189], v196 offset:3072
	ds_read_b128 v[198:201], v196 offset:4096
	ds_read_b128 v[202:205], v196 offset:5120
	ds_read_b128 v[206:209], v196 offset:6144
	ds_read_b128 v[210:213], v196 offset:7168
	global_load_lds_dwordx4 v[190:191], off
	v_lshl_add_u64 v[190:191], s[20:21], 0, v[136:137]
	s_add_i32 m0, s19, 0xe000
	s_nop 0
	global_load_lds_dwordx4 v[190:191], off
	s_waitcnt vmcnt(8)
	s_waitcnt lgkmcnt(0)
	s_barrier
	s_setprio 0
	s_waitcnt lgkmcnt(0)
	v_mfma_f32_16x16x32_bf16 v[126:129], v[142:145], v[174:177], v[126:129]
	v_mfma_f32_16x16x32_bf16 v[122:125], v[150:153], v[174:177], v[122:125]
	v_mfma_f32_16x16x32_bf16 v[114:117], v[142:145], v[182:185], v[114:117]
	v_mfma_f32_16x16x32_bf16 v[106:109], v[150:153], v[182:185], v[106:109]
	v_mfma_f32_16x16x32_bf16 v[98:101], v[142:145], v[198:201], v[98:101]
	v_mfma_f32_16x16x32_bf16 v[90:93], v[150:153], v[198:201], v[90:93]
	v_mfma_f32_16x16x32_bf16 v[82:85], v[142:145], v[206:209], v[82:85]
	v_mfma_f32_16x16x32_bf16 v[74:77], v[150:153], v[206:209], v[74:77]
	v_mfma_f32_16x16x32_bf16 v[126:129], v[146:149], v[178:181], v[126:129]
	v_mfma_f32_16x16x32_bf16 v[122:125], v[154:157], v[178:181], v[122:125]
	v_mfma_f32_16x16x32_bf16 v[114:117], v[146:149], v[186:189], v[114:117]
	v_mfma_f32_16x16x32_bf16 v[106:109], v[154:157], v[186:189], v[106:109]
	v_mfma_f32_16x16x32_bf16 v[98:101], v[146:149], v[202:205], v[98:101]
	v_mfma_f32_16x16x32_bf16 v[90:93], v[154:157], v[202:205], v[90:93]
	v_mfma_f32_16x16x32_bf16 v[82:85], v[146:149], v[210:213], v[82:85]
	v_mfma_f32_16x16x32_bf16 v[74:77], v[154:157], v[210:213], v[74:77]
	v_mfma_f32_16x16x32_bf16 v[118:121], v[158:161], v[174:177], v[118:121]
	v_mfma_f32_16x16x32_bf16 v[110:113], v[166:169], v[174:177], v[110:113]
	v_mfma_f32_16x16x32_bf16 v[102:105], v[158:161], v[182:185], v[102:105]
	v_mfma_f32_16x16x32_bf16 v[94:97], v[166:169], v[182:185], v[94:97]
	v_mfma_f32_16x16x32_bf16 v[86:89], v[158:161], v[198:201], v[86:89]
	v_mfma_f32_16x16x32_bf16 v[78:81], v[166:169], v[198:201], v[78:81]
	v_mfma_f32_16x16x32_bf16 v[70:73], v[158:161], v[206:209], v[70:73]
	v_mfma_f32_16x16x32_bf16 v[66:69], v[166:169], v[206:209], v[66:69]
	v_mfma_f32_16x16x32_bf16 v[118:121], v[162:165], v[178:181], v[118:121]
	v_mfma_f32_16x16x32_bf16 v[110:113], v[170:173], v[178:181], v[110:113]
	v_mfma_f32_16x16x32_bf16 v[102:105], v[162:165], v[186:189], v[102:105]
	v_mfma_f32_16x16x32_bf16 v[94:97], v[170:173], v[186:189], v[94:97]
	v_mfma_f32_16x16x32_bf16 v[86:89], v[162:165], v[202:205], v[86:89]
	v_mfma_f32_16x16x32_bf16 v[78:81], v[170:173], v[202:205], v[78:81]
	v_mfma_f32_16x16x32_bf16 v[70:73], v[162:165], v[210:213], v[70:73]
	v_mfma_f32_16x16x32_bf16 v[66:69], v[170:173], v[210:213], v[66:69]
	s_setprio 1
	s_barrier
	s_add_i32 s44, s80, s27
	v_lshl_add_u64 v[190:191], s[22:23], 0, v[130:131]
	s_mov_b32 m0, s44
	ds_read_b128 v[174:177], v196 offset:16384
	ds_read_b128 v[178:181], v196 offset:17408
	ds_read_b128 v[182:185], v196 offset:18432
	ds_read_b128 v[186:189], v196 offset:19456
	ds_read_b128 v[198:201], v196 offset:20480
	ds_read_b128 v[202:205], v196 offset:21504
	ds_read_b128 v[206:209], v196 offset:22528
	ds_read_b128 v[210:213], v196 offset:23552
	global_load_lds_dwordx4 v[190:191], off
	s_add_i32 m0, s44, 0x2000
	s_add_u32 s44, s22, 0x100000
	v_lshl_add_u64 v[214:215], s[22:23], 0, v[132:133]
	s_addc_u32 s45, s23, 0
	s_add_i32 s46, s37, s27
	global_load_lds_dwordx4 v[214:215], off
	v_lshl_add_u64 v[216:217], s[44:45], 0, v[130:131]
	s_mov_b32 m0, s46
	v_lshl_add_u64 v[218:219], s[24:25], 0, v[132:133]
	global_load_lds_dwordx4 v[216:217], off
	v_lshl_add_u64 v[216:217], s[44:45], 0, v[132:133]
	s_add_i32 m0, s46, 0x2000
	s_nop 0
	global_load_lds_dwordx4 v[216:217], off
	v_lshl_add_u64 v[216:217], s[24:25], 0, v[130:131]
	s_mov_b32 m0, s19
	s_nop 0
	global_load_lds_dwordx4 v[216:217], off
	s_mov_b32 m0, s28
	s_nop 0
	global_load_lds_dwordx4 v[218:219], off
	s_waitcnt vmcnt(8)
	s_waitcnt lgkmcnt(0)
	s_barrier
	s_setprio 0
	s_waitcnt lgkmcnt(0)
	v_mfma_f32_16x16x32_bf16 v[62:65], v[142:145], v[174:177], v[62:65]
	v_mfma_f32_16x16x32_bf16 v[58:61], v[150:153], v[174:177], v[58:61]
	v_mfma_f32_16x16x32_bf16 v[50:53], v[142:145], v[182:185], v[50:53]
	v_mfma_f32_16x16x32_bf16 v[42:45], v[150:153], v[182:185], v[42:45]
	v_mfma_f32_16x16x32_bf16 v[34:37], v[142:145], v[198:201], v[34:37]
	v_mfma_f32_16x16x32_bf16 v[26:29], v[150:153], v[198:201], v[26:29]
	v_mfma_f32_16x16x32_bf16 v[18:21], v[142:145], v[206:209], v[18:21]
	v_mfma_f32_16x16x32_bf16 v[10:13], v[150:153], v[206:209], v[10:13]
	v_mfma_f32_16x16x32_bf16 v[62:65], v[146:149], v[178:181], v[62:65]
	v_mfma_f32_16x16x32_bf16 v[58:61], v[154:157], v[178:181], v[58:61]
	v_mfma_f32_16x16x32_bf16 v[50:53], v[146:149], v[186:189], v[50:53]
	v_mfma_f32_16x16x32_bf16 v[42:45], v[154:157], v[186:189], v[42:45]
	v_mfma_f32_16x16x32_bf16 v[34:37], v[146:149], v[202:205], v[34:37]
	v_mfma_f32_16x16x32_bf16 v[26:29], v[154:157], v[202:205], v[26:29]
	v_mfma_f32_16x16x32_bf16 v[18:21], v[146:149], v[210:213], v[18:21]
	v_mfma_f32_16x16x32_bf16 v[10:13], v[154:157], v[210:213], v[10:13]
	v_mfma_f32_16x16x32_bf16 v[54:57], v[158:161], v[174:177], v[54:57]
	v_mfma_f32_16x16x32_bf16 v[46:49], v[166:169], v[174:177], v[46:49]
	v_mfma_f32_16x16x32_bf16 v[38:41], v[158:161], v[182:185], v[38:41]
	v_mfma_f32_16x16x32_bf16 v[30:33], v[166:169], v[182:185], v[30:33]
	v_mfma_f32_16x16x32_bf16 v[22:25], v[158:161], v[198:201], v[22:25]
	v_mfma_f32_16x16x32_bf16 v[14:17], v[166:169], v[198:201], v[14:17]
	v_mfma_f32_16x16x32_bf16 v[6:9], v[158:161], v[206:209], v[6:9]
	v_mfma_f32_16x16x32_bf16 v[2:5], v[166:169], v[206:209], v[2:5]
	v_mfma_f32_16x16x32_bf16 v[54:57], v[162:165], v[178:181], v[54:57]
	v_mfma_f32_16x16x32_bf16 v[46:49], v[170:173], v[178:181], v[46:49]
	v_mfma_f32_16x16x32_bf16 v[38:41], v[162:165], v[186:189], v[38:41]
	v_mfma_f32_16x16x32_bf16 v[30:33], v[170:173], v[186:189], v[30:33]
	v_mfma_f32_16x16x32_bf16 v[22:25], v[162:165], v[202:205], v[22:25]
	v_mfma_f32_16x16x32_bf16 v[14:17], v[170:173], v[202:205], v[14:17]
	v_mfma_f32_16x16x32_bf16 v[6:9], v[162:165], v[210:213], v[6:9]
	v_mfma_f32_16x16x32_bf16 v[2:5], v[170:173], v[210:213], v[2:5]
	s_setprio 1
	s_barrier
	s_add_i32 s44, 0, 0x18000
	s_add_i32 s45, 0, 0x1c000
	v_add_u32_e32 v154, s44, v192
	v_add_u32_e32 v170, s45, v192
	ds_read_b128 v[142:145], v154
	ds_read_b128 v[146:149], v154 offset:1024
	ds_read_b128 v[150:153], v154 offset:2048
	ds_read_b128 v[154:157], v154 offset:3072
	ds_read_b128 v[158:161], v170
	ds_read_b128 v[162:165], v170 offset:1024
	ds_read_b128 v[166:169], v170 offset:2048
	ds_read_b128 v[170:173], v170 offset:3072
	s_add_u32 s24, s24, 0x100000
	s_addc_u32 s25, s25, 0
	s_mov_b32 m0, s29
	v_lshl_add_u64 v[220:221], s[24:25], 0, v[130:131]
	ds_read_b128 v[174:177], v196 offset:32768
	ds_read_b128 v[178:181], v196 offset:33792
	ds_read_b128 v[182:185], v196 offset:34816
	ds_read_b128 v[186:189], v196 offset:35840
	ds_read_b128 v[198:201], v196 offset:36864
	ds_read_b128 v[202:205], v196 offset:37888
	ds_read_b128 v[206:209], v196 offset:38912
	ds_read_b128 v[210:213], v196 offset:39936
	global_load_lds_dwordx4 v[220:221], off
	v_lshl_add_u64 v[220:221], s[24:25], 0, v[132:133]
	s_mov_b32 m0, s30
	s_nop 0
	global_load_lds_dwordx4 v[220:221], off
	s_waitcnt vmcnt(8)
	s_waitcnt lgkmcnt(0)
	s_barrier
	s_setprio 0
	s_waitcnt lgkmcnt(0)
	v_mfma_f32_16x16x32_bf16 v[126:129], v[142:145], v[174:177], v[126:129]
	v_mfma_f32_16x16x32_bf16 v[122:125], v[150:153], v[174:177], v[122:125]
	v_mfma_f32_16x16x32_bf16 v[114:117], v[142:145], v[182:185], v[114:117]
	v_mfma_f32_16x16x32_bf16 v[106:109], v[150:153], v[182:185], v[106:109]
	v_mfma_f32_16x16x32_bf16 v[98:101], v[142:145], v[198:201], v[98:101]
	v_mfma_f32_16x16x32_bf16 v[90:93], v[150:153], v[198:201], v[90:93]
	v_mfma_f32_16x16x32_bf16 v[82:85], v[142:145], v[206:209], v[82:85]
	v_mfma_f32_16x16x32_bf16 v[74:77], v[150:153], v[206:209], v[74:77]
	v_mfma_f32_16x16x32_bf16 v[126:129], v[146:149], v[178:181], v[126:129]
	v_mfma_f32_16x16x32_bf16 v[122:125], v[154:157], v[178:181], v[122:125]
	v_mfma_f32_16x16x32_bf16 v[114:117], v[146:149], v[186:189], v[114:117]
	v_mfma_f32_16x16x32_bf16 v[106:109], v[154:157], v[186:189], v[106:109]
	v_mfma_f32_16x16x32_bf16 v[98:101], v[146:149], v[202:205], v[98:101]
	v_mfma_f32_16x16x32_bf16 v[90:93], v[154:157], v[202:205], v[90:93]
	v_mfma_f32_16x16x32_bf16 v[82:85], v[146:149], v[210:213], v[82:85]
	v_mfma_f32_16x16x32_bf16 v[74:77], v[154:157], v[210:213], v[74:77]
	v_mfma_f32_16x16x32_bf16 v[118:121], v[158:161], v[174:177], v[118:121]
	v_mfma_f32_16x16x32_bf16 v[110:113], v[166:169], v[174:177], v[110:113]
	v_mfma_f32_16x16x32_bf16 v[102:105], v[158:161], v[182:185], v[102:105]
	v_mfma_f32_16x16x32_bf16 v[94:97], v[166:169], v[182:185], v[94:97]
	v_mfma_f32_16x16x32_bf16 v[86:89], v[158:161], v[198:201], v[86:89]
	v_mfma_f32_16x16x32_bf16 v[78:81], v[166:169], v[198:201], v[78:81]
	v_mfma_f32_16x16x32_bf16 v[70:73], v[158:161], v[206:209], v[70:73]
	v_mfma_f32_16x16x32_bf16 v[66:69], v[166:169], v[206:209], v[66:69]
	v_mfma_f32_16x16x32_bf16 v[118:121], v[162:165], v[178:181], v[118:121]
	v_mfma_f32_16x16x32_bf16 v[110:113], v[170:173], v[178:181], v[110:113]
	v_mfma_f32_16x16x32_bf16 v[102:105], v[162:165], v[186:189], v[102:105]
	v_mfma_f32_16x16x32_bf16 v[94:97], v[170:173], v[186:189], v[94:97]
	v_mfma_f32_16x16x32_bf16 v[86:89], v[162:165], v[202:205], v[86:89]
	v_mfma_f32_16x16x32_bf16 v[78:81], v[170:173], v[202:205], v[78:81]
	v_mfma_f32_16x16x32_bf16 v[70:73], v[162:165], v[210:213], v[70:73]
	v_mfma_f32_16x16x32_bf16 v[66:69], v[170:173], v[210:213], v[66:69]
	s_setprio 1
	s_barrier
	s_add_i32 s24, s44, s27
	v_lshl_add_u64 v[190:191], v[190:191], 0, s[4:5]
	s_mov_b32 m0, s24
	ds_read_b128 v[174:177], v196 offset:49152
	ds_read_b128 v[178:181], v196 offset:50176
	ds_read_b128 v[182:185], v196 offset:51200
	ds_read_b128 v[186:189], v196 offset:52224
	ds_read_b128 v[198:201], v196 offset:53248
	ds_read_b128 v[202:205], v196 offset:54272
	ds_read_b128 v[206:209], v196 offset:55296
	ds_read_b128 v[210:213], v196 offset:56320
	global_load_lds_dwordx4 v[190:191], off
	s_add_i32 m0, s24, 0x2000
	s_add_u32 s22, s22, 0x100080
	v_lshl_add_u64 v[190:191], v[214:215], 0, s[4:5]
	s_addc_u32 s23, s23, 0
	s_add_i32 s24, s45, s27
	global_load_lds_dwordx4 v[190:191], off
	v_lshl_add_u64 v[190:191], s[22:23], 0, v[130:131]
	s_mov_b32 m0, s24
	s_nop 0
	global_load_lds_dwordx4 v[190:191], off
	v_lshl_add_u64 v[190:191], s[22:23], 0, v[132:133]
	s_add_i32 m0, s24, 0x2000
	s_nop 0
	global_load_lds_dwordx4 v[190:191], off
	v_lshl_add_u64 v[190:191], v[216:217], 0, s[4:5]
	s_mov_b32 m0, s34
	s_nop 0
	global_load_lds_dwordx4 v[190:191], off
	v_lshl_add_u64 v[190:191], v[218:219], 0, s[4:5]
	s_mov_b32 m0, s35
	s_nop 0
	global_load_lds_dwordx4 v[190:191], off
	s_waitcnt vmcnt(8)
	s_waitcnt lgkmcnt(0)
	s_barrier
	s_setprio 0
	s_waitcnt lgkmcnt(0)
	v_mfma_f32_16x16x32_bf16 v[62:65], v[142:145], v[174:177], v[62:65]
	v_mfma_f32_16x16x32_bf16 v[58:61], v[150:153], v[174:177], v[58:61]
	v_mfma_f32_16x16x32_bf16 v[50:53], v[142:145], v[182:185], v[50:53]
	v_mfma_f32_16x16x32_bf16 v[42:45], v[150:153], v[182:185], v[42:45]
	v_mfma_f32_16x16x32_bf16 v[34:37], v[142:145], v[198:201], v[34:37]
	v_mfma_f32_16x16x32_bf16 v[26:29], v[150:153], v[198:201], v[26:29]
	v_mfma_f32_16x16x32_bf16 v[18:21], v[142:145], v[206:209], v[18:21]
	v_mfma_f32_16x16x32_bf16 v[10:13], v[150:153], v[206:209], v[10:13]
	v_mfma_f32_16x16x32_bf16 v[62:65], v[146:149], v[178:181], v[62:65]
	v_mfma_f32_16x16x32_bf16 v[58:61], v[154:157], v[178:181], v[58:61]
	v_mfma_f32_16x16x32_bf16 v[50:53], v[146:149], v[186:189], v[50:53]
	v_mfma_f32_16x16x32_bf16 v[42:45], v[154:157], v[186:189], v[42:45]
	v_mfma_f32_16x16x32_bf16 v[34:37], v[146:149], v[202:205], v[34:37]
	v_mfma_f32_16x16x32_bf16 v[26:29], v[154:157], v[202:205], v[26:29]
	v_mfma_f32_16x16x32_bf16 v[18:21], v[146:149], v[210:213], v[18:21]
	v_mfma_f32_16x16x32_bf16 v[10:13], v[154:157], v[210:213], v[10:13]
	v_mfma_f32_16x16x32_bf16 v[54:57], v[158:161], v[174:177], v[54:57]
	v_mfma_f32_16x16x32_bf16 v[46:49], v[166:169], v[174:177], v[46:49]
	v_mfma_f32_16x16x32_bf16 v[38:41], v[158:161], v[182:185], v[38:41]
	v_mfma_f32_16x16x32_bf16 v[30:33], v[166:169], v[182:185], v[30:33]
	v_mfma_f32_16x16x32_bf16 v[22:25], v[158:161], v[198:201], v[22:25]
	v_mfma_f32_16x16x32_bf16 v[14:17], v[166:169], v[198:201], v[14:17]
	v_mfma_f32_16x16x32_bf16 v[6:9], v[158:161], v[206:209], v[6:9]
	v_mfma_f32_16x16x32_bf16 v[2:5], v[166:169], v[206:209], v[2:5]
	v_mfma_f32_16x16x32_bf16 v[54:57], v[162:165], v[178:181], v[54:57]
	v_mfma_f32_16x16x32_bf16 v[46:49], v[170:173], v[178:181], v[46:49]
	v_mfma_f32_16x16x32_bf16 v[38:41], v[162:165], v[186:189], v[38:41]
	v_mfma_f32_16x16x32_bf16 v[30:33], v[170:173], v[186:189], v[30:33]
	v_mfma_f32_16x16x32_bf16 v[22:25], v[162:165], v[202:205], v[22:25]
	v_mfma_f32_16x16x32_bf16 v[14:17], v[170:173], v[202:205], v[14:17]
	v_mfma_f32_16x16x32_bf16 v[6:9], v[162:165], v[210:213], v[6:9]
	v_mfma_f32_16x16x32_bf16 v[2:5], v[170:173], v[210:213], v[2:5]
	s_setprio 1
	s_barrier
	s_add_i32 s43, s43, 2
	s_add_u32 s20, s20, 0x100
	s_addc_u32 s21, s21, 0
	s_add_u32 s41, s41, 0x100
	s_addc_u32 s42, s42, 0
	s_cmp_gt_u32 s43, 61
	s_cbranch_scc0 .LBB0_1485
	s_and_b64 vcc, exec, s[6:7]
	s_cbranch_vccz .LBB0_1488
	s_barrier
